# strategy 9: K-loop induction SALU (counter and pointer increments) moved ahead of the loop-back barrier in all six GEMM loops, on top of v9
# baseline (speedup 1.0000x reference)
; #define PG8_STAGE(bufoff, gbase, voff) do { _Pragma("unroll") for (int _i = 0; _i < 2; ++_i) \
;         __builtin_amdgcn_global_load_lds((const unsigned*)((const char*)(gbase) + (voff)[_i]), (PG8_LAS unsigned*)(lds + (bufoff) + ldsw + _i * 8192), 16, 0, 0); } while (0)
; #define PG8_LDA(dst, b, h) do { _Pragma("unroll") for (int m = 0; m < 4; ++m) _Pragma("unroll") for (int k = 0; k < 2; ++k) dst[m][k] = *(const PG8_LAS bf16x8*)(lds + PG8_SA(b, h) + aoff + m * 2048 + k * 1024); } while (0)
; #define PG8_LDB(dst, b, h) do { _Pragma("unroll") for (int n = 0; n < 2; ++n) _Pragma("unroll") for (int k = 0; k < 2; ++k) dst[n][k] = *(const PG8_LAS bf16x8*)(lds + PG8_SB(b, h) + boff + n * 2048 + k * 1024); } while (0)
; #define PG8_MMA(ai, bj, At, Bt) do { __builtin_amdgcn_s_setprio(1); _Pragma("unroll") for (int m = 0; m < 4; ++m) _Pragma("unroll") for (int n = 0; n < 2; ++n) _Pragma("unroll") for (int k = 0; k < 2; ++k) \
;         acc[ai][bj][m][n] = __builtin_amdgcn_mfma_f32_16x16x32_bf16(Bt[n][k], At[m][k], acc[ai][bj][m][n], 0, 0, 0); __builtin_amdgcn_s_setprio(0); } while (0)
; #define PG8_WAIT_V(n) asm volatile("s_waitcnt vmcnt(" #n ")" ::: "memory")
; #define PG8_WAIT_L(n) asm volatile("s_waitcnt lgkmcnt(" #n ")" ::: "memory")
; template <class Epi, class Sched, bool ALIGN_EPI = false, bool SP2 = false>
; __device__ __forceinline__ void gemm_phase(PG8_LAS unsigned char* lds, const Gemm g, const Sched& S, const Epi& E) {
;     ...
;             const bool last = (t == nt - 2);
;             const char* a1 = cA + (size_t)(t + 1) * kstep;
;             const char* a2 = last ? nA : cA + (size_t)(t + 2) * kstep; const char* b2 = last ? nB : cB + (size_t)(t + 2) * kstep;
;             const char* a3 = a2 + kstep; const char* b3 = b2 + kstep;
;             if (last && has_next) S.a_ready(nxt);
;             if constexpr (SP2) {
;             PG8_LDB(B0, 0, 0); PG8_LDB(B1, 0, 1); PG8_SCHED; PG8_LDA(At, 0, 0); PG8_STAGE(PG8_SA(1, 1), a1 + hstep, voffA);
;             PG8_WAIT_V(8); PG8_WAIT_L(0); PG8_BAR; PG8_MMA(0, 0, At, B0); PG8_MMA(0, 1, At, B1); PG8_BAR; PG8_SCHED;
;             PG8_LDA(At, 0, 1); PG8_STAGE(PG8_SB(0, 0), b2, voffB); PG8_STAGE(PG8_SB(0, 1), b2 + hstep, voffB); PG8_STAGE(PG8_SA(0, 0), a2, voffA);
;             PG8_WAIT_V(8); PG8_WAIT_L(0); PG8_BAR; PG8_MMA(1, 0, At, B0); PG8_MMA(1, 1, At, B1); PG8_BAR; PG8_SCHED;
.LBB0_147:
	s_add_u32 s12, s56, 0xfff80080
	s_addc_u32 s13, s57, -1
	s_add_i32 s85, 0, 0x10000
	s_cmp_eq_u32 s84, 28
	s_cselect_b32 s61, s18, s13
	s_cselect_b32 s60, s19, s12
	v_add_u32_e32 v142, s85, v145
	s_cselect_b32 s59, s43, s73
	s_cselect_b32 s58, s47, s72
	s_add_i32 s92, 0, 0x14000
	ds_read_b128 v[148:151], v142
	ds_read_b128 v[152:155], v142 offset:1024
	ds_read_b128 v[156:159], v142 offset:2048
	ds_read_b128 v[160:163], v142 offset:3072
	v_add_u32_e32 v142, s92, v145
	ds_read_b128 v[164:167], v142
	ds_read_b128 v[168:171], v142 offset:1024
	ds_read_b128 v[172:175], v142 offset:2048
	ds_read_b128 v[176:179], v142 offset:3072
	v_lshl_add_u64 v[142:143], s[56:57], 0, v[140:141]
	s_add_i32 m0, s55, 0xc000
	ds_read_b128 v[180:183], v147
	ds_read_b128 v[184:187], v147 offset:1024
	ds_read_b128 v[188:191], v147 offset:2048
	ds_read_b128 v[202:205], v147 offset:3072
	ds_read_b128 v[206:209], v147 offset:4096
	ds_read_b128 v[210:213], v147 offset:5120
	ds_read_b128 v[214:217], v147 offset:6144
	ds_read_b128 v[218:221], v147 offset:7168
	global_load_lds_dwordx4 v[142:143], off
	v_lshl_add_u64 v[142:143], s[56:57], 0, v[138:139]
	s_add_i32 m0, s55, 0xe000
	s_nop 0
	global_load_lds_dwordx4 v[142:143], off
	s_waitcnt vmcnt(8)
	s_waitcnt lgkmcnt(0)
	s_barrier
	s_setprio 1
	s_waitcnt lgkmcnt(0)
	v_mfma_f32_16x16x32_bf16 v[126:129], v[148:151], v[180:183], v[126:129]
	v_mfma_f32_16x16x32_bf16 v[122:125], v[156:159], v[180:183], v[122:125]
	v_mfma_f32_16x16x32_bf16 v[118:121], v[148:151], v[188:191], v[118:121]
	v_mfma_f32_16x16x32_bf16 v[110:113], v[156:159], v[188:191], v[110:113]
	v_mfma_f32_16x16x32_bf16 v[102:105], v[148:151], v[206:209], v[102:105]
	v_mfma_f32_16x16x32_bf16 v[92:95], v[156:159], v[206:209], v[92:95]
	v_mfma_f32_16x16x32_bf16 v[84:87], v[148:151], v[214:217], v[84:87]
	v_mfma_f32_16x16x32_bf16 v[76:79], v[156:159], v[214:217], v[76:79]
	v_mfma_f32_16x16x32_bf16 v[126:129], v[152:155], v[184:187], v[126:129]
	v_mfma_f32_16x16x32_bf16 v[122:125], v[160:163], v[184:187], v[122:125]
	v_mfma_f32_16x16x32_bf16 v[118:121], v[152:155], v[202:205], v[118:121]
	v_mfma_f32_16x16x32_bf16 v[110:113], v[160:163], v[202:205], v[110:113]
	v_mfma_f32_16x16x32_bf16 v[102:105], v[152:155], v[210:213], v[102:105]
	v_mfma_f32_16x16x32_bf16 v[92:95], v[160:163], v[210:213], v[92:95]
	v_mfma_f32_16x16x32_bf16 v[84:87], v[152:155], v[218:221], v[84:87]
	v_mfma_f32_16x16x32_bf16 v[76:79], v[160:163], v[218:221], v[76:79]
	s_setprio 0
	s_setprio 1
	v_mfma_f32_16x16x32_bf16 v[114:117], v[164:167], v[180:183], v[114:117]
	v_mfma_f32_16x16x32_bf16 v[106:109], v[172:175], v[180:183], v[106:109]
	v_mfma_f32_16x16x32_bf16 v[98:101], v[164:167], v[188:191], v[98:101]
	v_mfma_f32_16x16x32_bf16 v[88:91], v[172:175], v[188:191], v[88:91]
	v_mfma_f32_16x16x32_bf16 v[80:83], v[164:167], v[206:209], v[80:83]
	v_mfma_f32_16x16x32_bf16 v[72:75], v[172:175], v[206:209], v[72:75]
	v_mfma_f32_16x16x32_bf16 v[68:71], v[164:167], v[214:217], v[68:71]
	v_mfma_f32_16x16x32_bf16 v[64:67], v[172:175], v[214:217], v[64:67]
	v_mfma_f32_16x16x32_bf16 v[114:117], v[168:171], v[184:187], v[114:117]
	v_mfma_f32_16x16x32_bf16 v[106:109], v[176:179], v[184:187], v[106:109]
	v_mfma_f32_16x16x32_bf16 v[98:101], v[168:171], v[202:205], v[98:101]
	v_mfma_f32_16x16x32_bf16 v[88:91], v[176:179], v[202:205], v[88:91]
	v_mfma_f32_16x16x32_bf16 v[80:83], v[168:171], v[210:213], v[80:83]
	v_mfma_f32_16x16x32_bf16 v[72:75], v[176:179], v[210:213], v[72:75]
	v_mfma_f32_16x16x32_bf16 v[68:71], v[168:171], v[218:221], v[68:71]
	v_mfma_f32_16x16x32_bf16 v[64:67], v[176:179], v[218:221], v[64:67]
	s_setprio 0
	s_barrier
	s_add_i32 s12, s85, s63
	v_lshl_add_u64 v[142:143], s[58:59], 0, v[132:133]
	s_mov_b32 m0, s12
	ds_read_b128 v[180:183], v147 offset:16384
	ds_read_b128 v[184:187], v147 offset:17408
	ds_read_b128 v[188:191], v147 offset:18432
	ds_read_b128 v[202:205], v147 offset:19456
	ds_read_b128 v[206:209], v147 offset:20480
	ds_read_b128 v[210:213], v147 offset:21504
	ds_read_b128 v[214:217], v147 offset:22528
	ds_read_b128 v[218:221], v147 offset:23552
	global_load_lds_dwordx4 v[142:143], off
	s_add_i32 m0, s12, 0x2000
	s_add_u32 s12, s58, 0x80000
	v_lshl_add_u64 v[192:193], s[58:59], 0, v[136:137]
	s_addc_u32 s13, s59, 0
	s_add_i32 s85, s92, s63
	global_load_lds_dwordx4 v[192:193], off
	v_lshl_add_u64 v[222:223], s[12:13], 0, v[132:133]
	s_mov_b32 m0, s85
	v_lshl_add_u64 v[224:225], s[60:61], 0, v[134:135]
	global_load_lds_dwordx4 v[222:223], off
	v_lshl_add_u64 v[222:223], s[12:13], 0, v[136:137]
	s_add_i32 m0, s85, 0x2000
	s_nop 0
	global_load_lds_dwordx4 v[222:223], off
	v_lshl_add_u64 v[222:223], s[60:61], 0, v[130:131]
	s_mov_b32 m0, s55
	s_nop 0
	global_load_lds_dwordx4 v[222:223], off
	s_mov_b32 m0, s64
	s_nop 0
	global_load_lds_dwordx4 v[224:225], off
	s_waitcnt vmcnt(8)
	s_waitcnt lgkmcnt(0)
	s_barrier
; #define PG8_STAGE(bufoff, gbase, voff) do { _Pragma("unroll") for (int _i = 0; _i < 2; ++_i) \
;         __builtin_amdgcn_global_load_lds((const unsigned*)((const char*)(gbase) + (voff)[_i]), (PG8_LAS unsigned*)(lds + (bufoff) + ldsw + _i * 8192), 16, 0, 0); } while (0)
; #define PG8_LDA(dst, b, h) do { _Pragma("unroll") for (int m = 0; m < 4; ++m) _Pragma("unroll") for (int k = 0; k < 2; ++k) dst[m][k] = *(const PG8_LAS bf16x8*)(lds + PG8_SA(b, h) + aoff + m * 2048 + k * 1024); } while (0)
; #define PG8_LDB(dst, b, h) do { _Pragma("unroll") for (int n = 0; n < 2; ++n) _Pragma("unroll") for (int k = 0; k < 2; ++k) dst[n][k] = *(const PG8_LAS bf16x8*)(lds + PG8_SB(b, h) + boff + n * 2048 + k * 1024); } while (0)
; #define PG8_MMA(ai, bj, At, Bt) do { __builtin_amdgcn_s_setprio(1); _Pragma("unroll") for (int m = 0; m < 4; ++m) _Pragma("unroll") for (int n = 0; n < 2; ++n) _Pragma("unroll") for (int k = 0; k < 2; ++k) \
;         acc[ai][bj][m][n] = __builtin_amdgcn_mfma_f32_16x16x32_bf16(Bt[n][k], At[m][k], acc[ai][bj][m][n], 0, 0, 0); __builtin_amdgcn_s_setprio(0); } while (0)
; #define PG8_WAIT_V(n) asm volatile("s_waitcnt vmcnt(" #n ")" ::: "memory")
; #define PG8_WAIT_L(n) asm volatile("s_waitcnt lgkmcnt(" #n ")" ::: "memory")
; #define PG8_BAR __builtin_amdgcn_s_barrier()
; #define PG8_SCHED __builtin_amdgcn_sched_barrier(0)
; template <class Epi, class Sched, bool ALIGN_EPI = false, bool SP2 = false>
; __device__ __forceinline__ void gemm_phase(PG8_LAS unsigned char* lds, const Gemm g, const Sched& S, const Epi& E) {
;     ...
;             PG8_WAIT_V(8); PG8_WAIT_L(0); PG8_BAR; PG8_MMA(1, 0, At, B0); PG8_MMA(1, 1, At, B1); PG8_BAR; PG8_SCHED;
;             PG8_LDB(B0, 1, 0); PG8_LDB(B1, 1, 1); PG8_SCHED; PG8_LDA(At, 1, 0); PG8_STAGE(PG8_SA(0, 1), a2 + hstep, voffA);
;             PG8_WAIT_V(8); PG8_WAIT_L(0); PG8_BAR; PG8_MMA(0, 0, At, B0); PG8_MMA(0, 1, At, B1); PG8_BAR; PG8_SCHED;
	s_setprio 1
	s_waitcnt lgkmcnt(0)
	v_mfma_f32_16x16x32_bf16 v[60:63], v[148:151], v[180:183], v[60:63]
	v_mfma_f32_16x16x32_bf16 v[56:59], v[156:159], v[180:183], v[56:59]
	v_mfma_f32_16x16x32_bf16 v[52:55], v[148:151], v[188:191], v[52:55]
	v_mfma_f32_16x16x32_bf16 v[44:47], v[156:159], v[188:191], v[44:47]
	v_mfma_f32_16x16x32_bf16 v[36:39], v[148:151], v[206:209], v[36:39]
	v_mfma_f32_16x16x32_bf16 v[28:31], v[156:159], v[206:209], v[28:31]
	v_mfma_f32_16x16x32_bf16 v[20:23], v[148:151], v[214:217], v[20:23]
	v_mfma_f32_16x16x32_bf16 v[12:15], v[156:159], v[214:217], v[12:15]
	v_mfma_f32_16x16x32_bf16 v[60:63], v[152:155], v[184:187], v[60:63]
	v_mfma_f32_16x16x32_bf16 v[56:59], v[160:163], v[184:187], v[56:59]
	v_mfma_f32_16x16x32_bf16 v[52:55], v[152:155], v[202:205], v[52:55]
	v_mfma_f32_16x16x32_bf16 v[44:47], v[160:163], v[202:205], v[44:47]
	v_mfma_f32_16x16x32_bf16 v[36:39], v[152:155], v[210:213], v[36:39]
	v_mfma_f32_16x16x32_bf16 v[28:31], v[160:163], v[210:213], v[28:31]
	v_mfma_f32_16x16x32_bf16 v[20:23], v[152:155], v[218:221], v[20:23]
	v_mfma_f32_16x16x32_bf16 v[12:15], v[160:163], v[218:221], v[12:15]
	s_setprio 0
	s_setprio 1
	v_mfma_f32_16x16x32_bf16 v[48:51], v[164:167], v[180:183], v[48:51]
	v_mfma_f32_16x16x32_bf16 v[40:43], v[172:175], v[180:183], v[40:43]
	v_mfma_f32_16x16x32_bf16 v[32:35], v[164:167], v[188:191], v[32:35]
	v_mfma_f32_16x16x32_bf16 v[24:27], v[172:175], v[188:191], v[24:27]
	v_mfma_f32_16x16x32_bf16 v[16:19], v[164:167], v[206:209], v[16:19]
	v_mfma_f32_16x16x32_bf16 v[8:11], v[172:175], v[206:209], v[8:11]
	v_mfma_f32_16x16x32_bf16 v[4:7], v[164:167], v[214:217], v[4:7]
	v_mfma_f32_16x16x32_bf16 v[0:3], v[172:175], v[214:217], v[0:3]
	v_mfma_f32_16x16x32_bf16 v[48:51], v[168:171], v[184:187], v[48:51]
	v_mfma_f32_16x16x32_bf16 v[40:43], v[176:179], v[184:187], v[40:43]
	v_mfma_f32_16x16x32_bf16 v[32:35], v[168:171], v[202:205], v[32:35]
	v_mfma_f32_16x16x32_bf16 v[24:27], v[176:179], v[202:205], v[24:27]
	v_mfma_f32_16x16x32_bf16 v[16:19], v[168:171], v[210:213], v[16:19]
	v_mfma_f32_16x16x32_bf16 v[8:11], v[176:179], v[210:213], v[8:11]
	v_mfma_f32_16x16x32_bf16 v[4:7], v[168:171], v[218:221], v[4:7]
	v_mfma_f32_16x16x32_bf16 v[0:3], v[176:179], v[218:221], v[0:3]
	s_setprio 0
	s_barrier
	s_add_i32 s85, 0, 0x18000
	s_add_i32 s92, 0, 0x1c000
	v_add_u32_e32 v160, s85, v145
	v_add_u32_e32 v176, s92, v145
	ds_read_b128 v[148:151], v160
	ds_read_b128 v[152:155], v160 offset:1024
	ds_read_b128 v[156:159], v160 offset:2048
	ds_read_b128 v[160:163], v160 offset:3072
	ds_read_b128 v[164:167], v176
	ds_read_b128 v[168:171], v176 offset:1024
	ds_read_b128 v[172:175], v176 offset:2048
	ds_read_b128 v[176:179], v176 offset:3072
	s_add_u32 s12, s60, 0x80000
	s_addc_u32 s13, s61, 0
	s_mov_b32 m0, s65
	v_lshl_add_u64 v[226:227], s[12:13], 0, v[130:131]
	ds_read_b128 v[180:183], v147 offset:32768
	ds_read_b128 v[184:187], v147 offset:33792
	ds_read_b128 v[188:191], v147 offset:34816
	ds_read_b128 v[202:205], v147 offset:35840
	ds_read_b128 v[206:209], v147 offset:36864
	ds_read_b128 v[210:213], v147 offset:37888
	ds_read_b128 v[214:217], v147 offset:38912
	ds_read_b128 v[218:221], v147 offset:39936
	global_load_lds_dwordx4 v[226:227], off
	v_lshl_add_u64 v[226:227], s[12:13], 0, v[134:135]
	s_mov_b32 m0, s67
	s_nop 0
	global_load_lds_dwordx4 v[226:227], off
	s_waitcnt vmcnt(8)
	s_waitcnt lgkmcnt(0)
	s_barrier
	s_setprio 1
	s_waitcnt lgkmcnt(0)
	v_mfma_f32_16x16x32_bf16 v[126:129], v[148:151], v[180:183], v[126:129]
	v_mfma_f32_16x16x32_bf16 v[122:125], v[156:159], v[180:183], v[122:125]
	v_mfma_f32_16x16x32_bf16 v[118:121], v[148:151], v[188:191], v[118:121]
	v_mfma_f32_16x16x32_bf16 v[110:113], v[156:159], v[188:191], v[110:113]
	v_mfma_f32_16x16x32_bf16 v[102:105], v[148:151], v[206:209], v[102:105]
	v_mfma_f32_16x16x32_bf16 v[92:95], v[156:159], v[206:209], v[92:95]
	v_mfma_f32_16x16x32_bf16 v[84:87], v[148:151], v[214:217], v[84:87]
	v_mfma_f32_16x16x32_bf16 v[76:79], v[156:159], v[214:217], v[76:79]
	v_mfma_f32_16x16x32_bf16 v[126:129], v[152:155], v[184:187], v[126:129]
	v_mfma_f32_16x16x32_bf16 v[122:125], v[160:163], v[184:187], v[122:125]
	v_mfma_f32_16x16x32_bf16 v[118:121], v[152:155], v[202:205], v[118:121]
	v_mfma_f32_16x16x32_bf16 v[110:113], v[160:163], v[202:205], v[110:113]
	v_mfma_f32_16x16x32_bf16 v[102:105], v[152:155], v[210:213], v[102:105]
	v_mfma_f32_16x16x32_bf16 v[92:95], v[160:163], v[210:213], v[92:95]
	v_mfma_f32_16x16x32_bf16 v[84:87], v[152:155], v[218:221], v[84:87]
	v_mfma_f32_16x16x32_bf16 v[76:79], v[160:163], v[218:221], v[76:79]
	s_setprio 0
	s_setprio 1
	v_mfma_f32_16x16x32_bf16 v[114:117], v[164:167], v[180:183], v[114:117]
	v_mfma_f32_16x16x32_bf16 v[106:109], v[172:175], v[180:183], v[106:109]
	v_mfma_f32_16x16x32_bf16 v[98:101], v[164:167], v[188:191], v[98:101]
	v_mfma_f32_16x16x32_bf16 v[88:91], v[172:175], v[188:191], v[88:91]
	v_mfma_f32_16x16x32_bf16 v[80:83], v[164:167], v[206:209], v[80:83]
	v_mfma_f32_16x16x32_bf16 v[72:75], v[172:175], v[206:209], v[72:75]
	v_mfma_f32_16x16x32_bf16 v[68:71], v[164:167], v[214:217], v[68:71]
	v_mfma_f32_16x16x32_bf16 v[64:67], v[172:175], v[214:217], v[64:67]
	v_mfma_f32_16x16x32_bf16 v[114:117], v[168:171], v[184:187], v[114:117]
	v_mfma_f32_16x16x32_bf16 v[106:109], v[176:179], v[184:187], v[106:109]
	v_mfma_f32_16x16x32_bf16 v[98:101], v[168:171], v[202:205], v[98:101]
	v_mfma_f32_16x16x32_bf16 v[88:91], v[176:179], v[202:205], v[88:91]
	v_mfma_f32_16x16x32_bf16 v[80:83], v[168:171], v[210:213], v[80:83]
	v_mfma_f32_16x16x32_bf16 v[72:75], v[176:179], v[210:213], v[72:75]
	v_mfma_f32_16x16x32_bf16 v[68:71], v[168:171], v[218:221], v[68:71]
	v_mfma_f32_16x16x32_bf16 v[64:67], v[176:179], v[218:221], v[64:67]
	s_setprio 0
	s_barrier
; #define PG8_STAGE(bufoff, gbase, voff) do { _Pragma("unroll") for (int _i = 0; _i < 2; ++_i) \
;         __builtin_amdgcn_global_load_lds((const unsigned*)((const char*)(gbase) + (voff)[_i]), (PG8_LAS unsigned*)(lds + (bufoff) + ldsw + _i * 8192), 16, 0, 0); } while (0)
; #define PG8_LDA(dst, b, h) do { _Pragma("unroll") for (int m = 0; m < 4; ++m) _Pragma("unroll") for (int k = 0; k < 2; ++k) dst[m][k] = *(const PG8_LAS bf16x8*)(lds + PG8_SA(b, h) + aoff + m * 2048 + k * 1024); } while (0)
; #define PG8_MMA(ai, bj, At, Bt) do { __builtin_amdgcn_s_setprio(1); _Pragma("unroll") for (int m = 0; m < 4; ++m) _Pragma("unroll") for (int n = 0; n < 2; ++n) _Pragma("unroll") for (int k = 0; k < 2; ++k) \
;         acc[ai][bj][m][n] = __builtin_amdgcn_mfma_f32_16x16x32_bf16(Bt[n][k], At[m][k], acc[ai][bj][m][n], 0, 0, 0); __builtin_amdgcn_s_setprio(0); } while (0)
; #define PG8_WAIT_V(n) asm volatile("s_waitcnt vmcnt(" #n ")" ::: "memory")
; #define PG8_WAIT_L(n) asm volatile("s_waitcnt lgkmcnt(" #n ")" ::: "memory")
; #define PG8_BAR __builtin_amdgcn_s_barrier()
; #define PG8_SCHED __builtin_amdgcn_sched_barrier(0)
; template <class Epi, class Sched, bool ALIGN_EPI = false, bool SP2 = false>
; __device__ __forceinline__ void gemm_phase(PG8_LAS unsigned char* lds, const Gemm g, const Sched& S, const Epi& E) {
;     ...
;         for (int t = 0; t < nt; t += 2) {
;     ...
;             PG8_LDA(At, 1, 1); PG8_STAGE(PG8_SB(1, 0), b3, voffB); PG8_STAGE(PG8_SB(1, 1), b3 + hstep, voffB); PG8_STAGE(PG8_SA(1, 0), a3, voffA);
;             PG8_WAIT_V(8); PG8_WAIT_L(0); PG8_BAR; PG8_MMA(1, 0, At, B0); PG8_MMA(1, 1, At, B1); PG8_BAR; PG8_SCHED;
	s_add_i32 s12, s85, s63
	v_lshl_add_u64 v[142:143], v[142:143], 0, s[36:37]
	s_mov_b32 m0, s12
	ds_read_b128 v[180:183], v147 offset:49152
	ds_read_b128 v[184:187], v147 offset:50176
	ds_read_b128 v[188:191], v147 offset:51200
	ds_read_b128 v[202:205], v147 offset:52224
	ds_read_b128 v[206:209], v147 offset:53248
	ds_read_b128 v[210:213], v147 offset:54272
	ds_read_b128 v[214:217], v147 offset:55296
	ds_read_b128 v[218:221], v147 offset:56320
	global_load_lds_dwordx4 v[142:143], off
	s_add_i32 m0, s12, 0x2000
	s_add_u32 s12, s58, 0x80080
	v_lshl_add_u64 v[142:143], v[192:193], 0, s[36:37]
	s_addc_u32 s13, s59, 0
	s_add_i32 s58, s92, s63
	global_load_lds_dwordx4 v[142:143], off
	v_lshl_add_u64 v[142:143], s[12:13], 0, v[132:133]
	s_mov_b32 m0, s58
	s_nop 0
	global_load_lds_dwordx4 v[142:143], off
	v_lshl_add_u64 v[142:143], s[12:13], 0, v[136:137]
	s_add_i32 m0, s58, 0x2000
	s_nop 0
	global_load_lds_dwordx4 v[142:143], off
	v_lshl_add_u64 v[142:143], v[222:223], 0, s[36:37]
	s_mov_b32 m0, s68
	s_nop 0
	global_load_lds_dwordx4 v[142:143], off
	v_lshl_add_u64 v[142:143], v[224:225], 0, s[36:37]
	s_mov_b32 m0, s69
	s_nop 0
	global_load_lds_dwordx4 v[142:143], off
	s_waitcnt vmcnt(8)
	s_waitcnt lgkmcnt(0)
	s_barrier
	s_setprio 1
	s_waitcnt lgkmcnt(0)
	v_mfma_f32_16x16x32_bf16 v[60:63], v[148:151], v[180:183], v[60:63]
	v_mfma_f32_16x16x32_bf16 v[56:59], v[156:159], v[180:183], v[56:59]
	v_mfma_f32_16x16x32_bf16 v[52:55], v[148:151], v[188:191], v[52:55]
	v_mfma_f32_16x16x32_bf16 v[44:47], v[156:159], v[188:191], v[44:47]
	v_mfma_f32_16x16x32_bf16 v[36:39], v[148:151], v[206:209], v[36:39]
	v_mfma_f32_16x16x32_bf16 v[28:31], v[156:159], v[206:209], v[28:31]
	v_mfma_f32_16x16x32_bf16 v[20:23], v[148:151], v[214:217], v[20:23]
	v_mfma_f32_16x16x32_bf16 v[12:15], v[156:159], v[214:217], v[12:15]
	v_mfma_f32_16x16x32_bf16 v[60:63], v[152:155], v[184:187], v[60:63]
	v_mfma_f32_16x16x32_bf16 v[56:59], v[160:163], v[184:187], v[56:59]
	v_mfma_f32_16x16x32_bf16 v[52:55], v[152:155], v[202:205], v[52:55]
	v_mfma_f32_16x16x32_bf16 v[44:47], v[160:163], v[202:205], v[44:47]
	v_mfma_f32_16x16x32_bf16 v[36:39], v[152:155], v[210:213], v[36:39]
	v_mfma_f32_16x16x32_bf16 v[28:31], v[160:163], v[210:213], v[28:31]
	v_mfma_f32_16x16x32_bf16 v[20:23], v[152:155], v[218:221], v[20:23]
	v_mfma_f32_16x16x32_bf16 v[12:15], v[160:163], v[218:221], v[12:15]
	s_setprio 0
	s_setprio 1
	v_mfma_f32_16x16x32_bf16 v[48:51], v[164:167], v[180:183], v[48:51]
	v_mfma_f32_16x16x32_bf16 v[40:43], v[172:175], v[180:183], v[40:43]
	v_mfma_f32_16x16x32_bf16 v[32:35], v[164:167], v[188:191], v[32:35]
	v_mfma_f32_16x16x32_bf16 v[24:27], v[172:175], v[188:191], v[24:27]
	v_mfma_f32_16x16x32_bf16 v[16:19], v[164:167], v[206:209], v[16:19]
	v_mfma_f32_16x16x32_bf16 v[8:11], v[172:175], v[206:209], v[8:11]
	v_mfma_f32_16x16x32_bf16 v[4:7], v[164:167], v[214:217], v[4:7]
	v_mfma_f32_16x16x32_bf16 v[0:3], v[172:175], v[214:217], v[0:3]
	v_mfma_f32_16x16x32_bf16 v[48:51], v[168:171], v[184:187], v[48:51]
	v_mfma_f32_16x16x32_bf16 v[40:43], v[176:179], v[184:187], v[40:43]
	v_mfma_f32_16x16x32_bf16 v[32:35], v[168:171], v[202:205], v[32:35]
	v_mfma_f32_16x16x32_bf16 v[24:27], v[176:179], v[202:205], v[24:27]
	v_mfma_f32_16x16x32_bf16 v[16:19], v[168:171], v[210:213], v[16:19]
	v_mfma_f32_16x16x32_bf16 v[8:11], v[176:179], v[210:213], v[8:11]
	v_mfma_f32_16x16x32_bf16 v[4:7], v[168:171], v[218:221], v[4:7]
	v_mfma_f32_16x16x32_bf16 v[0:3], v[176:179], v[218:221], v[0:3]
	s_setprio 0
	s_add_i32 s84, s84, 2
	s_add_u32 s72, s72, 0x100
	s_addc_u32 s73, s73, 0
	s_add_u32 s56, s56, 0x100
	s_addc_u32 s57, s57, 0
	s_barrier
	s_cmp_gt_u32 s84, 29
	s_cbranch_scc0 .LBB0_147
	s_and_b64 vcc, exec, s[14:15]
	s_cbranch_vccz .LBB0_150
	s_barrier

; #define PG8_STAGE(bufoff, gbase, voff) do { _Pragma("unroll") for (int _i = 0; _i < 2; ++_i) \
;         __builtin_amdgcn_global_load_lds((const unsigned*)((const char*)(gbase) + (voff)[_i]), (PG8_LAS unsigned*)(lds + (bufoff) + ldsw + _i * 8192), 16, 0, 0); } while (0)
; #define PG8_LDA(dst, b, h) do { _Pragma("unroll") for (int m = 0; m < 4; ++m) _Pragma("unroll") for (int k = 0; k < 2; ++k) dst[m][k] = *(const PG8_LAS bf16x8*)(lds + PG8_SA(b, h) + aoff + m * 2048 + k * 1024); } while (0)
; #define PG8_LDB(dst, b, h) do { _Pragma("unroll") for (int n = 0; n < 2; ++n) _Pragma("unroll") for (int k = 0; k < 2; ++k) dst[n][k] = *(const PG8_LAS bf16x8*)(lds + PG8_SB(b, h) + boff + n * 2048 + k * 1024); } while (0)
; #define PG8_MMA(ai, bj, At, Bt) do { __builtin_amdgcn_s_setprio(1); _Pragma("unroll") for (int m = 0; m < 4; ++m) _Pragma("unroll") for (int n = 0; n < 2; ++n) _Pragma("unroll") for (int k = 0; k < 2; ++k) \
;         acc[ai][bj][m][n] = __builtin_amdgcn_mfma_f32_16x16x32_bf16(Bt[n][k], At[m][k], acc[ai][bj][m][n], 0, 0, 0); __builtin_amdgcn_s_setprio(0); } while (0)
; #define PG8_WAIT_V(n) asm volatile("s_waitcnt vmcnt(" #n ")" ::: "memory")
; #define PG8_WAIT_L(n) asm volatile("s_waitcnt lgkmcnt(" #n ")" ::: "memory")
; template <class Epi, class Sched, bool ALIGN_EPI = false, bool SP2 = false>
; __device__ __forceinline__ void gemm_phase(PG8_LAS unsigned char* lds, const Gemm g, const Sched& S, const Epi& E) {
;     ...
;             const bool last = (t == nt - 2);
;             const char* a1 = cA + (size_t)(t + 1) * kstep;
;             const char* a2 = last ? nA : cA + (size_t)(t + 2) * kstep; const char* b2 = last ? nB : cB + (size_t)(t + 2) * kstep;
;             const char* a3 = a2 + kstep; const char* b3 = b2 + kstep;
;             if (last && has_next) S.a_ready(nxt);
;             if constexpr (SP2) {
;             PG8_LDB(B0, 0, 0); PG8_LDB(B1, 0, 1); PG8_SCHED; PG8_LDA(At, 0, 0); PG8_STAGE(PG8_SA(1, 1), a1 + hstep, voffA);
;             PG8_WAIT_V(8); PG8_WAIT_L(0); PG8_BAR; PG8_MMA(0, 0, At, B0); PG8_MMA(0, 1, At, B1); PG8_BAR; PG8_SCHED;
;             PG8_LDA(At, 0, 1); PG8_STAGE(PG8_SB(0, 0), b2, voffB); PG8_STAGE(PG8_SB(0, 1), b2 + hstep, voffB); PG8_STAGE(PG8_SA(0, 0), a2, voffA);
;             PG8_WAIT_V(8); PG8_WAIT_L(0); PG8_BAR; PG8_MMA(1, 0, At, B0); PG8_MMA(1, 1, At, B1); PG8_BAR; PG8_SCHED;
.LBB0_175:
	s_add_u32 s12, s42, 0xfff80080
	s_addc_u32 s13, s43, -1
	s_add_i32 vcc_lo, 0, 0x10000
	s_cmp_eq_u32 s55, 28
	s_cselect_b32 s65, s10, s13
	s_cselect_b32 s64, s11, s12
	v_add_u32_e32 v148, vcc_lo, v150
	s_cselect_b32 s63, s5, s19
	s_cselect_b32 s62, s15, s18
	s_add_i32 vcc_hi, 0, 0x14000
	ds_read_b128 v[144:147], v148
	ds_read_b128 v[154:157], v148 offset:1024
	ds_read_b128 v[158:161], v148 offset:2048
	ds_read_b128 v[162:165], v148 offset:3072
	v_add_u32_e32 v148, vcc_hi, v150
	ds_read_b128 v[166:169], v148
	ds_read_b128 v[170:173], v148 offset:1024
	ds_read_b128 v[174:177], v148 offset:2048
	ds_read_b128 v[178:181], v148 offset:3072
	v_lshl_add_u64 v[222:223], s[42:43], 0, v[142:143]
	s_add_i32 m0, s61, 0xc000
	ds_read_b128 v[182:185], v153
	ds_read_b128 v[186:189], v153 offset:1024
	ds_read_b128 v[190:193], v153 offset:2048
	ds_read_b128 v[202:205], v153 offset:3072
	ds_read_b128 v[206:209], v153 offset:4096
	ds_read_b128 v[210:213], v153 offset:5120
	ds_read_b128 v[214:217], v153 offset:6144
	ds_read_b128 v[218:221], v153 offset:7168
	global_load_lds_dwordx4 v[222:223], off
	v_lshl_add_u64 v[222:223], s[42:43], 0, v[140:141]
	s_add_i32 m0, s61, 0xe000
	s_nop 0
	global_load_lds_dwordx4 v[222:223], off
	s_waitcnt vmcnt(8)
	s_waitcnt lgkmcnt(0)
	s_barrier
	s_setprio 1
	s_waitcnt lgkmcnt(0)
	v_mfma_f32_16x16x32_bf16 v[126:129], v[144:147], v[182:185], v[126:129]
	v_mfma_f32_16x16x32_bf16 v[122:125], v[158:161], v[182:185], v[122:125]
	v_mfma_f32_16x16x32_bf16 v[110:113], v[144:147], v[190:193], v[110:113]
	v_mfma_f32_16x16x32_bf16 v[106:109], v[158:161], v[190:193], v[106:109]
	v_mfma_f32_16x16x32_bf16 v[92:95], v[144:147], v[206:209], v[92:95]
	v_mfma_f32_16x16x32_bf16 v[88:91], v[158:161], v[206:209], v[88:91]
	v_mfma_f32_16x16x32_bf16 v[76:79], v[144:147], v[214:217], v[76:79]
	v_mfma_f32_16x16x32_bf16 v[72:75], v[158:161], v[214:217], v[72:75]
	v_mfma_f32_16x16x32_bf16 v[126:129], v[154:157], v[186:189], v[126:129]
	v_mfma_f32_16x16x32_bf16 v[122:125], v[162:165], v[186:189], v[122:125]
	v_mfma_f32_16x16x32_bf16 v[110:113], v[154:157], v[202:205], v[110:113]
	v_mfma_f32_16x16x32_bf16 v[106:109], v[162:165], v[202:205], v[106:109]
	v_mfma_f32_16x16x32_bf16 v[92:95], v[154:157], v[210:213], v[92:95]
	v_mfma_f32_16x16x32_bf16 v[88:91], v[162:165], v[210:213], v[88:91]
	v_mfma_f32_16x16x32_bf16 v[76:79], v[154:157], v[218:221], v[76:79]
	v_mfma_f32_16x16x32_bf16 v[72:75], v[162:165], v[218:221], v[72:75]
	s_setprio 0
	s_setprio 1
	v_mfma_f32_16x16x32_bf16 v[118:121], v[166:169], v[182:185], v[118:121]
	v_mfma_f32_16x16x32_bf16 v[114:117], v[174:177], v[182:185], v[114:117]
	v_mfma_f32_16x16x32_bf16 v[102:105], v[166:169], v[190:193], v[102:105]
	v_mfma_f32_16x16x32_bf16 v[98:101], v[174:177], v[190:193], v[98:101]
	v_mfma_f32_16x16x32_bf16 v[84:87], v[166:169], v[206:209], v[84:87]
	v_mfma_f32_16x16x32_bf16 v[80:83], v[174:177], v[206:209], v[80:83]
	v_mfma_f32_16x16x32_bf16 v[68:71], v[166:169], v[214:217], v[68:71]
	v_mfma_f32_16x16x32_bf16 v[64:67], v[174:177], v[214:217], v[64:67]
	v_mfma_f32_16x16x32_bf16 v[118:121], v[170:173], v[186:189], v[118:121]
	v_mfma_f32_16x16x32_bf16 v[114:117], v[178:181], v[186:189], v[114:117]
	v_mfma_f32_16x16x32_bf16 v[102:105], v[170:173], v[202:205], v[102:105]
	v_mfma_f32_16x16x32_bf16 v[98:101], v[178:181], v[202:205], v[98:101]
	v_mfma_f32_16x16x32_bf16 v[84:87], v[170:173], v[210:213], v[84:87]
	v_mfma_f32_16x16x32_bf16 v[80:83], v[178:181], v[210:213], v[80:83]
	v_mfma_f32_16x16x32_bf16 v[68:71], v[170:173], v[218:221], v[68:71]
	v_mfma_f32_16x16x32_bf16 v[64:67], v[178:181], v[218:221], v[64:67]
	s_setprio 0
	s_barrier
	s_add_i32 s12, vcc_lo, s70
	v_lshl_add_u64 v[222:223], s[62:63], 0, v[132:133]
	s_mov_b32 m0, s12
	ds_read_b128 v[182:185], v153 offset:16384
	ds_read_b128 v[186:189], v153 offset:17408
	ds_read_b128 v[190:193], v153 offset:18432
	ds_read_b128 v[202:205], v153 offset:19456
	ds_read_b128 v[206:209], v153 offset:20480
	ds_read_b128 v[210:213], v153 offset:21504
	ds_read_b128 v[214:217], v153 offset:22528
	ds_read_b128 v[218:221], v153 offset:23552
	global_load_lds_dwordx4 v[222:223], off
	s_add_i32 m0, s12, 0x2000
	s_add_u32 s12, s62, 0x80000
	v_lshl_add_u64 v[224:225], s[62:63], 0, v[136:137]
	s_addc_u32 s13, s63, 0
	s_add_i32 vcc_lo, vcc_hi, s70
	global_load_lds_dwordx4 v[224:225], off
	v_lshl_add_u64 v[226:227], s[12:13], 0, v[132:133]
	s_mov_b32 m0, vcc_lo
	v_lshl_add_u64 v[228:229], s[64:65], 0, v[134:135]
	global_load_lds_dwordx4 v[226:227], off
	v_lshl_add_u64 v[226:227], s[12:13], 0, v[136:137]
	s_add_i32 m0, vcc_lo, 0x2000
	s_nop 0
	global_load_lds_dwordx4 v[226:227], off
	v_lshl_add_u64 v[226:227], s[64:65], 0, v[130:131]
	s_mov_b32 m0, s61
	s_nop 0
	global_load_lds_dwordx4 v[226:227], off
	s_mov_b32 m0, s72
	s_nop 0
	global_load_lds_dwordx4 v[228:229], off
	s_waitcnt vmcnt(8)
	s_waitcnt lgkmcnt(0)
	s_barrier
; #define PG8_STAGE(bufoff, gbase, voff) do { _Pragma("unroll") for (int _i = 0; _i < 2; ++_i) \
;         __builtin_amdgcn_global_load_lds((const unsigned*)((const char*)(gbase) + (voff)[_i]), (PG8_LAS unsigned*)(lds + (bufoff) + ldsw + _i * 8192), 16, 0, 0); } while (0)
; #define PG8_LDA(dst, b, h) do { _Pragma("unroll") for (int m = 0; m < 4; ++m) _Pragma("unroll") for (int k = 0; k < 2; ++k) dst[m][k] = *(const PG8_LAS bf16x8*)(lds + PG8_SA(b, h) + aoff + m * 2048 + k * 1024); } while (0)
; #define PG8_LDB(dst, b, h) do { _Pragma("unroll") for (int n = 0; n < 2; ++n) _Pragma("unroll") for (int k = 0; k < 2; ++k) dst[n][k] = *(const PG8_LAS bf16x8*)(lds + PG8_SB(b, h) + boff + n * 2048 + k * 1024); } while (0)
; #define PG8_MMA(ai, bj, At, Bt) do { __builtin_amdgcn_s_setprio(1); _Pragma("unroll") for (int m = 0; m < 4; ++m) _Pragma("unroll") for (int n = 0; n < 2; ++n) _Pragma("unroll") for (int k = 0; k < 2; ++k) \
;         acc[ai][bj][m][n] = __builtin_amdgcn_mfma_f32_16x16x32_bf16(Bt[n][k], At[m][k], acc[ai][bj][m][n], 0, 0, 0); __builtin_amdgcn_s_setprio(0); } while (0)
; #define PG8_WAIT_V(n) asm volatile("s_waitcnt vmcnt(" #n ")" ::: "memory")
; #define PG8_WAIT_L(n) asm volatile("s_waitcnt lgkmcnt(" #n ")" ::: "memory")
; #define PG8_BAR __builtin_amdgcn_s_barrier()
; #define PG8_SCHED __builtin_amdgcn_sched_barrier(0)
; template <class Epi, class Sched, bool ALIGN_EPI = false, bool SP2 = false>
; __device__ __forceinline__ void gemm_phase(PG8_LAS unsigned char* lds, const Gemm g, const Sched& S, const Epi& E) {
;     ...
;             PG8_WAIT_V(8); PG8_WAIT_L(0); PG8_BAR; PG8_MMA(1, 0, At, B0); PG8_MMA(1, 1, At, B1); PG8_BAR; PG8_SCHED;
;             PG8_LDB(B0, 1, 0); PG8_LDB(B1, 1, 1); PG8_SCHED; PG8_LDA(At, 1, 0); PG8_STAGE(PG8_SA(0, 1), a2 + hstep, voffA);
;             PG8_WAIT_V(8); PG8_WAIT_L(0); PG8_BAR; PG8_MMA(0, 0, At, B0); PG8_MMA(0, 1, At, B1); PG8_BAR; PG8_SCHED;
	s_setprio 1
	s_waitcnt lgkmcnt(0)
	v_mfma_f32_16x16x32_bf16 v[60:63], v[144:147], v[182:185], v[60:63]
	v_mfma_f32_16x16x32_bf16 v[56:59], v[158:161], v[182:185], v[56:59]
	v_mfma_f32_16x16x32_bf16 v[44:47], v[144:147], v[190:193], v[44:47]
	v_mfma_f32_16x16x32_bf16 v[40:43], v[158:161], v[190:193], v[40:43]
	v_mfma_f32_16x16x32_bf16 v[28:31], v[144:147], v[206:209], v[28:31]
	v_mfma_f32_16x16x32_bf16 v[24:27], v[158:161], v[206:209], v[24:27]
	v_mfma_f32_16x16x32_bf16 v[12:15], v[144:147], v[214:217], v[12:15]
	v_mfma_f32_16x16x32_bf16 v[8:11], v[158:161], v[214:217], v[8:11]
	v_mfma_f32_16x16x32_bf16 v[60:63], v[154:157], v[186:189], v[60:63]
	v_mfma_f32_16x16x32_bf16 v[56:59], v[162:165], v[186:189], v[56:59]
	v_mfma_f32_16x16x32_bf16 v[44:47], v[154:157], v[202:205], v[44:47]
	v_mfma_f32_16x16x32_bf16 v[40:43], v[162:165], v[202:205], v[40:43]
	v_mfma_f32_16x16x32_bf16 v[28:31], v[154:157], v[210:213], v[28:31]
	v_mfma_f32_16x16x32_bf16 v[24:27], v[162:165], v[210:213], v[24:27]
	v_mfma_f32_16x16x32_bf16 v[12:15], v[154:157], v[218:221], v[12:15]
	v_mfma_f32_16x16x32_bf16 v[8:11], v[162:165], v[218:221], v[8:11]
	s_setprio 0
	s_setprio 1
	v_mfma_f32_16x16x32_bf16 v[52:55], v[166:169], v[182:185], v[52:55]
	v_mfma_f32_16x16x32_bf16 v[48:51], v[174:177], v[182:185], v[48:51]
	v_mfma_f32_16x16x32_bf16 v[36:39], v[166:169], v[190:193], v[36:39]
	v_mfma_f32_16x16x32_bf16 v[32:35], v[174:177], v[190:193], v[32:35]
	v_mfma_f32_16x16x32_bf16 v[20:23], v[166:169], v[206:209], v[20:23]
	v_mfma_f32_16x16x32_bf16 v[16:19], v[174:177], v[206:209], v[16:19]
	v_mfma_f32_16x16x32_bf16 v[4:7], v[166:169], v[214:217], v[4:7]
	v_mfma_f32_16x16x32_bf16 v[0:3], v[174:177], v[214:217], v[0:3]
	v_mfma_f32_16x16x32_bf16 v[52:55], v[170:173], v[186:189], v[52:55]
	v_mfma_f32_16x16x32_bf16 v[48:51], v[178:181], v[186:189], v[48:51]
	v_mfma_f32_16x16x32_bf16 v[36:39], v[170:173], v[202:205], v[36:39]
	v_mfma_f32_16x16x32_bf16 v[32:35], v[178:181], v[202:205], v[32:35]
	v_mfma_f32_16x16x32_bf16 v[20:23], v[170:173], v[210:213], v[20:23]
	v_mfma_f32_16x16x32_bf16 v[16:19], v[178:181], v[210:213], v[16:19]
	v_mfma_f32_16x16x32_bf16 v[4:7], v[170:173], v[218:221], v[4:7]
	v_mfma_f32_16x16x32_bf16 v[0:3], v[178:181], v[218:221], v[0:3]
	s_setprio 0
	s_barrier
	s_add_i32 vcc_lo, 0, 0x18000
	v_add_u32_e32 v148, vcc_lo, v150
	s_add_i32 vcc_hi, 0, 0x1c000
	ds_read_b128 v[144:147], v148
	ds_read_b128 v[154:157], v148 offset:1024
	ds_read_b128 v[158:161], v148 offset:2048
	ds_read_b128 v[162:165], v148 offset:3072
	v_add_u32_e32 v148, vcc_hi, v150
	ds_read_b128 v[166:169], v148
	ds_read_b128 v[170:173], v148 offset:1024
	ds_read_b128 v[174:177], v148 offset:2048
	ds_read_b128 v[178:181], v148 offset:3072
	s_add_u32 s12, s64, 0x80000
	s_addc_u32 s13, s65, 0
	s_mov_b32 m0, s73
	v_lshl_add_u64 v[230:231], s[12:13], 0, v[130:131]
	ds_read_b128 v[182:185], v153 offset:32768
	ds_read_b128 v[186:189], v153 offset:33792
	ds_read_b128 v[190:193], v153 offset:34816
	ds_read_b128 v[202:205], v153 offset:35840
	ds_read_b128 v[206:209], v153 offset:36864
	ds_read_b128 v[210:213], v153 offset:37888
	ds_read_b128 v[214:217], v153 offset:38912
	ds_read_b128 v[218:221], v153 offset:39936
	global_load_lds_dwordx4 v[230:231], off
	v_lshl_add_u64 v[230:231], s[12:13], 0, v[134:135]
	s_mov_b32 m0, s84
	s_nop 0
	global_load_lds_dwordx4 v[230:231], off
	s_waitcnt vmcnt(8)
	s_waitcnt lgkmcnt(0)
	s_barrier
	s_setprio 1
	s_waitcnt lgkmcnt(0)
	v_mfma_f32_16x16x32_bf16 v[126:129], v[144:147], v[182:185], v[126:129]
	v_mfma_f32_16x16x32_bf16 v[122:125], v[158:161], v[182:185], v[122:125]
	v_mfma_f32_16x16x32_bf16 v[110:113], v[144:147], v[190:193], v[110:113]
	v_mfma_f32_16x16x32_bf16 v[106:109], v[158:161], v[190:193], v[106:109]
	v_mfma_f32_16x16x32_bf16 v[92:95], v[144:147], v[206:209], v[92:95]
	v_mfma_f32_16x16x32_bf16 v[88:91], v[158:161], v[206:209], v[88:91]
	v_mfma_f32_16x16x32_bf16 v[76:79], v[144:147], v[214:217], v[76:79]
	v_mfma_f32_16x16x32_bf16 v[72:75], v[158:161], v[214:217], v[72:75]
	v_mfma_f32_16x16x32_bf16 v[126:129], v[154:157], v[186:189], v[126:129]
	v_mfma_f32_16x16x32_bf16 v[122:125], v[162:165], v[186:189], v[122:125]
	v_mfma_f32_16x16x32_bf16 v[110:113], v[154:157], v[202:205], v[110:113]
	v_mfma_f32_16x16x32_bf16 v[106:109], v[162:165], v[202:205], v[106:109]
	v_mfma_f32_16x16x32_bf16 v[92:95], v[154:157], v[210:213], v[92:95]
	v_mfma_f32_16x16x32_bf16 v[88:91], v[162:165], v[210:213], v[88:91]
	v_mfma_f32_16x16x32_bf16 v[76:79], v[154:157], v[218:221], v[76:79]
	v_mfma_f32_16x16x32_bf16 v[72:75], v[162:165], v[218:221], v[72:75]
	s_setprio 0
	s_setprio 1
	v_mfma_f32_16x16x32_bf16 v[118:121], v[166:169], v[182:185], v[118:121]
	v_mfma_f32_16x16x32_bf16 v[114:117], v[174:177], v[182:185], v[114:117]
	v_mfma_f32_16x16x32_bf16 v[102:105], v[166:169], v[190:193], v[102:105]
	v_mfma_f32_16x16x32_bf16 v[98:101], v[174:177], v[190:193], v[98:101]
	v_mfma_f32_16x16x32_bf16 v[84:87], v[166:169], v[206:209], v[84:87]
	v_mfma_f32_16x16x32_bf16 v[80:83], v[174:177], v[206:209], v[80:83]
	v_mfma_f32_16x16x32_bf16 v[68:71], v[166:169], v[214:217], v[68:71]
	v_mfma_f32_16x16x32_bf16 v[64:67], v[174:177], v[214:217], v[64:67]
	v_mfma_f32_16x16x32_bf16 v[118:121], v[170:173], v[186:189], v[118:121]
	v_mfma_f32_16x16x32_bf16 v[114:117], v[178:181], v[186:189], v[114:117]
	v_mfma_f32_16x16x32_bf16 v[102:105], v[170:173], v[202:205], v[102:105]
	v_mfma_f32_16x16x32_bf16 v[98:101], v[178:181], v[202:205], v[98:101]
	v_mfma_f32_16x16x32_bf16 v[84:87], v[170:173], v[210:213], v[84:87]
	v_mfma_f32_16x16x32_bf16 v[80:83], v[178:181], v[210:213], v[80:83]
	v_mfma_f32_16x16x32_bf16 v[68:71], v[170:173], v[218:221], v[68:71]
	v_mfma_f32_16x16x32_bf16 v[64:67], v[178:181], v[218:221], v[64:67]
	s_setprio 0
	s_barrier
; #define PG8_STAGE(bufoff, gbase, voff) do { _Pragma("unroll") for (int _i = 0; _i < 2; ++_i) \
;         __builtin_amdgcn_global_load_lds((const unsigned*)((const char*)(gbase) + (voff)[_i]), (PG8_LAS unsigned*)(lds + (bufoff) + ldsw + _i * 8192), 16, 0, 0); } while (0)
; #define PG8_LDA(dst, b, h) do { _Pragma("unroll") for (int m = 0; m < 4; ++m) _Pragma("unroll") for (int k = 0; k < 2; ++k) dst[m][k] = *(const PG8_LAS bf16x8*)(lds + PG8_SA(b, h) + aoff + m * 2048 + k * 1024); } while (0)
; #define PG8_MMA(ai, bj, At, Bt) do { __builtin_amdgcn_s_setprio(1); _Pragma("unroll") for (int m = 0; m < 4; ++m) _Pragma("unroll") for (int n = 0; n < 2; ++n) _Pragma("unroll") for (int k = 0; k < 2; ++k) \
;         acc[ai][bj][m][n] = __builtin_amdgcn_mfma_f32_16x16x32_bf16(Bt[n][k], At[m][k], acc[ai][bj][m][n], 0, 0, 0); __builtin_amdgcn_s_setprio(0); } while (0)
; #define PG8_WAIT_V(n) asm volatile("s_waitcnt vmcnt(" #n ")" ::: "memory")
; #define PG8_WAIT_L(n) asm volatile("s_waitcnt lgkmcnt(" #n ")" ::: "memory")
; #define PG8_BAR __builtin_amdgcn_s_barrier()
; #define PG8_SCHED __builtin_amdgcn_sched_barrier(0)
; template <class Epi, class Sched, bool ALIGN_EPI = false, bool SP2 = false>
; __device__ __forceinline__ void gemm_phase(PG8_LAS unsigned char* lds, const Gemm g, const Sched& S, const Epi& E) {
;     ...
;         for (int t = 0; t < nt; t += 2) {
;     ...
;             PG8_LDA(At, 1, 1); PG8_STAGE(PG8_SB(1, 0), b3, voffB); PG8_STAGE(PG8_SB(1, 1), b3 + hstep, voffB); PG8_STAGE(PG8_SA(1, 0), a3, voffA);
;             PG8_WAIT_V(8); PG8_WAIT_L(0); PG8_BAR; PG8_MMA(1, 0, At, B0); PG8_MMA(1, 1, At, B1); PG8_BAR; PG8_SCHED;
	s_add_i32 s12, vcc_lo, s70
	v_lshl_add_u64 v[222:223], v[222:223], 0, s[36:37]
	s_mov_b32 m0, s12
	ds_read_b128 v[182:185], v153 offset:49152
	ds_read_b128 v[186:189], v153 offset:50176
	ds_read_b128 v[190:193], v153 offset:51200
	ds_read_b128 v[202:205], v153 offset:52224
	ds_read_b128 v[206:209], v153 offset:53248
	ds_read_b128 v[210:213], v153 offset:54272
	ds_read_b128 v[214:217], v153 offset:55296
	ds_read_b128 v[218:221], v153 offset:56320
	global_load_lds_dwordx4 v[222:223], off
	s_add_i32 m0, s12, 0x2000
	s_add_u32 s12, s62, 0x80080
	v_lshl_add_u64 v[222:223], v[224:225], 0, s[36:37]
	s_addc_u32 s13, s63, 0
	s_add_i32 s62, vcc_hi, s70
	global_load_lds_dwordx4 v[222:223], off
	v_lshl_add_u64 v[222:223], s[12:13], 0, v[132:133]
	s_mov_b32 m0, s62
	s_nop 0
	global_load_lds_dwordx4 v[222:223], off
	v_lshl_add_u64 v[222:223], s[12:13], 0, v[136:137]
	s_add_i32 m0, s62, 0x2000
	s_nop 0
	global_load_lds_dwordx4 v[222:223], off
	v_lshl_add_u64 v[222:223], v[226:227], 0, s[36:37]
	s_mov_b32 m0, s85
	s_nop 0
	global_load_lds_dwordx4 v[222:223], off
	v_lshl_add_u64 v[222:223], v[228:229], 0, s[36:37]
	s_mov_b32 m0, s92
	s_nop 0
	global_load_lds_dwordx4 v[222:223], off
	s_waitcnt vmcnt(8)
	s_waitcnt lgkmcnt(0)
	s_barrier
	s_setprio 1
	s_waitcnt lgkmcnt(0)
	v_mfma_f32_16x16x32_bf16 v[60:63], v[144:147], v[182:185], v[60:63]
	v_mfma_f32_16x16x32_bf16 v[56:59], v[158:161], v[182:185], v[56:59]
	v_mfma_f32_16x16x32_bf16 v[44:47], v[144:147], v[190:193], v[44:47]
	v_mfma_f32_16x16x32_bf16 v[40:43], v[158:161], v[190:193], v[40:43]
	v_mfma_f32_16x16x32_bf16 v[28:31], v[144:147], v[206:209], v[28:31]
	v_mfma_f32_16x16x32_bf16 v[24:27], v[158:161], v[206:209], v[24:27]
	v_mfma_f32_16x16x32_bf16 v[12:15], v[144:147], v[214:217], v[12:15]
	v_mfma_f32_16x16x32_bf16 v[8:11], v[158:161], v[214:217], v[8:11]
	v_mfma_f32_16x16x32_bf16 v[60:63], v[154:157], v[186:189], v[60:63]
	v_mfma_f32_16x16x32_bf16 v[56:59], v[162:165], v[186:189], v[56:59]
	v_mfma_f32_16x16x32_bf16 v[44:47], v[154:157], v[202:205], v[44:47]
	v_mfma_f32_16x16x32_bf16 v[40:43], v[162:165], v[202:205], v[40:43]
	v_mfma_f32_16x16x32_bf16 v[28:31], v[154:157], v[210:213], v[28:31]
	v_mfma_f32_16x16x32_bf16 v[24:27], v[162:165], v[210:213], v[24:27]
	v_mfma_f32_16x16x32_bf16 v[12:15], v[154:157], v[218:221], v[12:15]
	v_mfma_f32_16x16x32_bf16 v[8:11], v[162:165], v[218:221], v[8:11]
	s_setprio 0
	s_setprio 1
	v_mfma_f32_16x16x32_bf16 v[52:55], v[166:169], v[182:185], v[52:55]
	v_mfma_f32_16x16x32_bf16 v[48:51], v[174:177], v[182:185], v[48:51]
	v_mfma_f32_16x16x32_bf16 v[36:39], v[166:169], v[190:193], v[36:39]
	v_mfma_f32_16x16x32_bf16 v[32:35], v[174:177], v[190:193], v[32:35]
	v_mfma_f32_16x16x32_bf16 v[20:23], v[166:169], v[206:209], v[20:23]
	v_mfma_f32_16x16x32_bf16 v[16:19], v[174:177], v[206:209], v[16:19]
	v_mfma_f32_16x16x32_bf16 v[4:7], v[166:169], v[214:217], v[4:7]
	v_mfma_f32_16x16x32_bf16 v[0:3], v[174:177], v[214:217], v[0:3]
	v_mfma_f32_16x16x32_bf16 v[52:55], v[170:173], v[186:189], v[52:55]
	v_mfma_f32_16x16x32_bf16 v[48:51], v[178:181], v[186:189], v[48:51]
	v_mfma_f32_16x16x32_bf16 v[36:39], v[170:173], v[202:205], v[36:39]
	v_mfma_f32_16x16x32_bf16 v[32:35], v[178:181], v[202:205], v[32:35]
	v_mfma_f32_16x16x32_bf16 v[20:23], v[170:173], v[210:213], v[20:23]
	v_mfma_f32_16x16x32_bf16 v[16:19], v[178:181], v[210:213], v[16:19]
	v_mfma_f32_16x16x32_bf16 v[4:7], v[170:173], v[218:221], v[4:7]
	v_mfma_f32_16x16x32_bf16 v[0:3], v[178:181], v[218:221], v[0:3]
	s_setprio 0
	s_add_i32 s55, s55, 2
	s_add_u32 s18, s18, 0x100
	s_addc_u32 s19, s19, 0
	s_add_u32 s42, s42, 0x100
	s_addc_u32 s43, s43, 0
	s_barrier
	s_cmp_gt_u32 s55, 29
	s_cbranch_scc0 .LBB0_175
	s_and_b64 vcc, exec, s[0:1]
	s_cbranch_vccz .LBB0_178
	s_barrier

; #define PG8_STAGE(bufoff, gbase, voff) do { _Pragma("unroll") for (int _i = 0; _i < 2; ++_i) \
;         __builtin_amdgcn_global_load_lds((const unsigned*)((const char*)(gbase) + (voff)[_i]), (PG8_LAS unsigned*)(lds + (bufoff) + ldsw + _i * 8192), 16, 0, 0); } while (0)
; #define PG8_LDA(dst, b, h) do { _Pragma("unroll") for (int m = 0; m < 4; ++m) _Pragma("unroll") for (int k = 0; k < 2; ++k) dst[m][k] = *(const PG8_LAS bf16x8*)(lds + PG8_SA(b, h) + aoff + m * 2048 + k * 1024); } while (0)
; #define PG8_LDB(dst, b, h) do { _Pragma("unroll") for (int n = 0; n < 2; ++n) _Pragma("unroll") for (int k = 0; k < 2; ++k) dst[n][k] = *(const PG8_LAS bf16x8*)(lds + PG8_SB(b, h) + boff + n * 2048 + k * 1024); } while (0)
; #define PG8_MMA(ai, bj, At, Bt) do { __builtin_amdgcn_s_setprio(1); _Pragma("unroll") for (int m = 0; m < 4; ++m) _Pragma("unroll") for (int n = 0; n < 2; ++n) _Pragma("unroll") for (int k = 0; k < 2; ++k) \
;         acc[ai][bj][m][n] = __builtin_amdgcn_mfma_f32_16x16x32_bf16(Bt[n][k], At[m][k], acc[ai][bj][m][n], 0, 0, 0); __builtin_amdgcn_s_setprio(0); } while (0)
; #define PG8_WAIT_V(n) asm volatile("s_waitcnt vmcnt(" #n ")" ::: "memory")
; #define PG8_WAIT_L(n) asm volatile("s_waitcnt lgkmcnt(" #n ")" ::: "memory")
; template <class Epi, class Sched, bool ALIGN_EPI = false, bool SP2 = false>
; __device__ __forceinline__ void gemm_phase(PG8_LAS unsigned char* lds, const Gemm g, const Sched& S, const Epi& E) {
;     ...
;             const bool last = (t == nt - 2);
;             const char* a1 = cA + (size_t)(t + 1) * kstep;
;             const char* a2 = last ? nA : cA + (size_t)(t + 2) * kstep; const char* b2 = last ? nB : cB + (size_t)(t + 2) * kstep;
;             const char* a3 = a2 + kstep; const char* b3 = b2 + kstep;
;             if (last && has_next) S.a_ready(nxt);
;             if constexpr (SP2) {
;             PG8_LDB(B0, 0, 0); PG8_LDB(B1, 0, 1); PG8_SCHED; PG8_LDA(At, 0, 0); PG8_STAGE(PG8_SA(1, 1), a1 + hstep, voffA);
;             PG8_WAIT_V(8); PG8_WAIT_L(0); PG8_BAR; PG8_MMA(0, 0, At, B0); PG8_MMA(0, 1, At, B1); PG8_BAR; PG8_SCHED;
;             PG8_LDA(At, 0, 1); PG8_STAGE(PG8_SB(0, 0), b2, voffB); PG8_STAGE(PG8_SB(0, 1), b2 + hstep, voffB); PG8_STAGE(PG8_SA(0, 0), a2, voffA);
;             PG8_WAIT_V(8); PG8_WAIT_L(0); PG8_BAR; PG8_MMA(1, 0, At, B0); PG8_MMA(1, 1, At, B1); PG8_BAR; PG8_SCHED;
.LBB0_236:
	s_add_u32 s12, s42, 0xfff80080
	s_addc_u32 s13, s43, -1
	s_add_i32 s73, 0, 0x10000
	s_cmp_eq_u32 s51, 28
	s_cselect_b32 s61, s10, s13
	s_cselect_b32 s60, s11, s12
	v_add_u32_e32 v148, s73, v149
	s_cselect_b32 s59, s5, s19
	s_cselect_b32 s58, s15, s18
	s_add_i32 s84, 0, 0x14000
	ds_read_b128 v[144:147], v148
	ds_read_b128 v[154:157], v148 offset:1024
	ds_read_b128 v[158:161], v148 offset:2048
	ds_read_b128 v[162:165], v148 offset:3072
	v_add_u32_e32 v148, s84, v149
	ds_read_b128 v[166:169], v148
	ds_read_b128 v[170:173], v148 offset:1024
	ds_read_b128 v[174:177], v148 offset:2048
	ds_read_b128 v[178:181], v148 offset:3072
	v_lshl_add_u64 v[222:223], s[42:43], 0, v[142:143]
	s_add_i32 m0, s57, 0xc000
	ds_read_b128 v[182:185], v152
	ds_read_b128 v[186:189], v152 offset:1024
	ds_read_b128 v[190:193], v152 offset:2048
	ds_read_b128 v[202:205], v152 offset:3072
	ds_read_b128 v[206:209], v152 offset:4096
	ds_read_b128 v[210:213], v152 offset:5120
	ds_read_b128 v[214:217], v152 offset:6144
	ds_read_b128 v[218:221], v152 offset:7168
	global_load_lds_dwordx4 v[222:223], off
	v_lshl_add_u64 v[222:223], s[42:43], 0, v[140:141]
	s_add_i32 m0, s57, 0xe000
	s_nop 0
	global_load_lds_dwordx4 v[222:223], off
	s_waitcnt vmcnt(8)
	s_waitcnt lgkmcnt(0)
	s_barrier
	s_setprio 1
	s_waitcnt lgkmcnt(0)
	v_mfma_f32_16x16x32_bf16 v[126:129], v[144:147], v[182:185], v[126:129]
	v_mfma_f32_16x16x32_bf16 v[122:125], v[158:161], v[182:185], v[122:125]
	v_mfma_f32_16x16x32_bf16 v[110:113], v[144:147], v[190:193], v[110:113]
	v_mfma_f32_16x16x32_bf16 v[106:109], v[158:161], v[190:193], v[106:109]
	v_mfma_f32_16x16x32_bf16 v[92:95], v[144:147], v[206:209], v[92:95]
	v_mfma_f32_16x16x32_bf16 v[88:91], v[158:161], v[206:209], v[88:91]
	v_mfma_f32_16x16x32_bf16 v[76:79], v[144:147], v[214:217], v[76:79]
	v_mfma_f32_16x16x32_bf16 v[72:75], v[158:161], v[214:217], v[72:75]
	v_mfma_f32_16x16x32_bf16 v[126:129], v[154:157], v[186:189], v[126:129]
	v_mfma_f32_16x16x32_bf16 v[122:125], v[162:165], v[186:189], v[122:125]
	v_mfma_f32_16x16x32_bf16 v[110:113], v[154:157], v[202:205], v[110:113]
	v_mfma_f32_16x16x32_bf16 v[106:109], v[162:165], v[202:205], v[106:109]
	v_mfma_f32_16x16x32_bf16 v[92:95], v[154:157], v[210:213], v[92:95]
	v_mfma_f32_16x16x32_bf16 v[88:91], v[162:165], v[210:213], v[88:91]
	v_mfma_f32_16x16x32_bf16 v[76:79], v[154:157], v[218:221], v[76:79]
	v_mfma_f32_16x16x32_bf16 v[72:75], v[162:165], v[218:221], v[72:75]
	s_setprio 0
	s_setprio 1
	v_mfma_f32_16x16x32_bf16 v[118:121], v[166:169], v[182:185], v[118:121]
	v_mfma_f32_16x16x32_bf16 v[114:117], v[174:177], v[182:185], v[114:117]
	v_mfma_f32_16x16x32_bf16 v[102:105], v[166:169], v[190:193], v[102:105]
	v_mfma_f32_16x16x32_bf16 v[98:101], v[174:177], v[190:193], v[98:101]
	v_mfma_f32_16x16x32_bf16 v[84:87], v[166:169], v[206:209], v[84:87]
	v_mfma_f32_16x16x32_bf16 v[80:83], v[174:177], v[206:209], v[80:83]
	v_mfma_f32_16x16x32_bf16 v[68:71], v[166:169], v[214:217], v[68:71]
	v_mfma_f32_16x16x32_bf16 v[64:67], v[174:177], v[214:217], v[64:67]
	v_mfma_f32_16x16x32_bf16 v[118:121], v[170:173], v[186:189], v[118:121]
	v_mfma_f32_16x16x32_bf16 v[114:117], v[178:181], v[186:189], v[114:117]
	v_mfma_f32_16x16x32_bf16 v[102:105], v[170:173], v[202:205], v[102:105]
	v_mfma_f32_16x16x32_bf16 v[98:101], v[178:181], v[202:205], v[98:101]
	v_mfma_f32_16x16x32_bf16 v[84:87], v[170:173], v[210:213], v[84:87]
	v_mfma_f32_16x16x32_bf16 v[80:83], v[178:181], v[210:213], v[80:83]
	v_mfma_f32_16x16x32_bf16 v[68:71], v[170:173], v[218:221], v[68:71]
	v_mfma_f32_16x16x32_bf16 v[64:67], v[178:181], v[218:221], v[64:67]
	s_setprio 0
	s_barrier
	s_add_i32 s12, s73, s9
	v_lshl_add_u64 v[222:223], s[58:59], 0, v[132:133]
	s_mov_b32 m0, s12
	ds_read_b128 v[182:185], v152 offset:16384
	ds_read_b128 v[186:189], v152 offset:17408
	ds_read_b128 v[190:193], v152 offset:18432
	ds_read_b128 v[202:205], v152 offset:19456
	ds_read_b128 v[206:209], v152 offset:20480
	ds_read_b128 v[210:213], v152 offset:21504
	ds_read_b128 v[214:217], v152 offset:22528
	ds_read_b128 v[218:221], v152 offset:23552
	global_load_lds_dwordx4 v[222:223], off
	s_add_i32 m0, s12, 0x2000
	s_add_u32 s12, s58, 0x80000
	v_lshl_add_u64 v[224:225], s[58:59], 0, v[136:137]
	s_addc_u32 s13, s59, 0
	s_add_i32 s73, s84, s9
	global_load_lds_dwordx4 v[224:225], off
	v_lshl_add_u64 v[226:227], s[12:13], 0, v[132:133]
	s_mov_b32 m0, s73
	v_lshl_add_u64 v[228:229], s[60:61], 0, v[134:135]
	global_load_lds_dwordx4 v[226:227], off
	v_lshl_add_u64 v[226:227], s[12:13], 0, v[136:137]
	s_add_i32 m0, s73, 0x2000
	s_nop 0
	global_load_lds_dwordx4 v[226:227], off
	v_lshl_add_u64 v[226:227], s[60:61], 0, v[130:131]
	s_mov_b32 m0, s57
	s_nop 0
	global_load_lds_dwordx4 v[226:227], off
	s_mov_b32 m0, s63
	s_nop 0
	global_load_lds_dwordx4 v[228:229], off
	s_waitcnt vmcnt(8)
	s_waitcnt lgkmcnt(0)
	s_barrier
; #define PG8_STAGE(bufoff, gbase, voff) do { _Pragma("unroll") for (int _i = 0; _i < 2; ++_i) \
;         __builtin_amdgcn_global_load_lds((const unsigned*)((const char*)(gbase) + (voff)[_i]), (PG8_LAS unsigned*)(lds + (bufoff) + ldsw + _i * 8192), 16, 0, 0); } while (0)
; #define PG8_LDA(dst, b, h) do { _Pragma("unroll") for (int m = 0; m < 4; ++m) _Pragma("unroll") for (int k = 0; k < 2; ++k) dst[m][k] = *(const PG8_LAS bf16x8*)(lds + PG8_SA(b, h) + aoff + m * 2048 + k * 1024); } while (0)
; #define PG8_LDB(dst, b, h) do { _Pragma("unroll") for (int n = 0; n < 2; ++n) _Pragma("unroll") for (int k = 0; k < 2; ++k) dst[n][k] = *(const PG8_LAS bf16x8*)(lds + PG8_SB(b, h) + boff + n * 2048 + k * 1024); } while (0)
; #define PG8_MMA(ai, bj, At, Bt) do { __builtin_amdgcn_s_setprio(1); _Pragma("unroll") for (int m = 0; m < 4; ++m) _Pragma("unroll") for (int n = 0; n < 2; ++n) _Pragma("unroll") for (int k = 0; k < 2; ++k) \
;         acc[ai][bj][m][n] = __builtin_amdgcn_mfma_f32_16x16x32_bf16(Bt[n][k], At[m][k], acc[ai][bj][m][n], 0, 0, 0); __builtin_amdgcn_s_setprio(0); } while (0)
; #define PG8_WAIT_V(n) asm volatile("s_waitcnt vmcnt(" #n ")" ::: "memory")
; #define PG8_WAIT_L(n) asm volatile("s_waitcnt lgkmcnt(" #n ")" ::: "memory")
; #define PG8_BAR __builtin_amdgcn_s_barrier()
; #define PG8_SCHED __builtin_amdgcn_sched_barrier(0)
; template <class Epi, class Sched, bool ALIGN_EPI = false, bool SP2 = false>
; __device__ __forceinline__ void gemm_phase(PG8_LAS unsigned char* lds, const Gemm g, const Sched& S, const Epi& E) {
;     ...
;             PG8_WAIT_V(8); PG8_WAIT_L(0); PG8_BAR; PG8_MMA(1, 0, At, B0); PG8_MMA(1, 1, At, B1); PG8_BAR; PG8_SCHED;
;             PG8_LDB(B0, 1, 0); PG8_LDB(B1, 1, 1); PG8_SCHED; PG8_LDA(At, 1, 0); PG8_STAGE(PG8_SA(0, 1), a2 + hstep, voffA);
;             PG8_WAIT_V(8); PG8_WAIT_L(0); PG8_BAR; PG8_MMA(0, 0, At, B0); PG8_MMA(0, 1, At, B1); PG8_BAR; PG8_SCHED;
	s_setprio 1
	s_waitcnt lgkmcnt(0)
	v_mfma_f32_16x16x32_bf16 v[60:63], v[144:147], v[182:185], v[60:63]
	v_mfma_f32_16x16x32_bf16 v[56:59], v[158:161], v[182:185], v[56:59]
	v_mfma_f32_16x16x32_bf16 v[44:47], v[144:147], v[190:193], v[44:47]
	v_mfma_f32_16x16x32_bf16 v[40:43], v[158:161], v[190:193], v[40:43]
	v_mfma_f32_16x16x32_bf16 v[28:31], v[144:147], v[206:209], v[28:31]
	v_mfma_f32_16x16x32_bf16 v[24:27], v[158:161], v[206:209], v[24:27]
	v_mfma_f32_16x16x32_bf16 v[12:15], v[144:147], v[214:217], v[12:15]
	v_mfma_f32_16x16x32_bf16 v[8:11], v[158:161], v[214:217], v[8:11]
	v_mfma_f32_16x16x32_bf16 v[60:63], v[154:157], v[186:189], v[60:63]
	v_mfma_f32_16x16x32_bf16 v[56:59], v[162:165], v[186:189], v[56:59]
	v_mfma_f32_16x16x32_bf16 v[44:47], v[154:157], v[202:205], v[44:47]
	v_mfma_f32_16x16x32_bf16 v[40:43], v[162:165], v[202:205], v[40:43]
	v_mfma_f32_16x16x32_bf16 v[28:31], v[154:157], v[210:213], v[28:31]
	v_mfma_f32_16x16x32_bf16 v[24:27], v[162:165], v[210:213], v[24:27]
	v_mfma_f32_16x16x32_bf16 v[12:15], v[154:157], v[218:221], v[12:15]
	v_mfma_f32_16x16x32_bf16 v[8:11], v[162:165], v[218:221], v[8:11]
	s_setprio 0
	s_setprio 1
	v_mfma_f32_16x16x32_bf16 v[52:55], v[166:169], v[182:185], v[52:55]
	v_mfma_f32_16x16x32_bf16 v[48:51], v[174:177], v[182:185], v[48:51]
	v_mfma_f32_16x16x32_bf16 v[36:39], v[166:169], v[190:193], v[36:39]
	v_mfma_f32_16x16x32_bf16 v[32:35], v[174:177], v[190:193], v[32:35]
	v_mfma_f32_16x16x32_bf16 v[20:23], v[166:169], v[206:209], v[20:23]
	v_mfma_f32_16x16x32_bf16 v[16:19], v[174:177], v[206:209], v[16:19]
	v_mfma_f32_16x16x32_bf16 v[4:7], v[166:169], v[214:217], v[4:7]
	v_mfma_f32_16x16x32_bf16 v[0:3], v[174:177], v[214:217], v[0:3]
	v_mfma_f32_16x16x32_bf16 v[52:55], v[170:173], v[186:189], v[52:55]
	v_mfma_f32_16x16x32_bf16 v[48:51], v[178:181], v[186:189], v[48:51]
	v_mfma_f32_16x16x32_bf16 v[36:39], v[170:173], v[202:205], v[36:39]
	v_mfma_f32_16x16x32_bf16 v[32:35], v[178:181], v[202:205], v[32:35]
	v_mfma_f32_16x16x32_bf16 v[20:23], v[170:173], v[210:213], v[20:23]
	v_mfma_f32_16x16x32_bf16 v[16:19], v[178:181], v[210:213], v[16:19]
	v_mfma_f32_16x16x32_bf16 v[4:7], v[170:173], v[218:221], v[4:7]
	v_mfma_f32_16x16x32_bf16 v[0:3], v[178:181], v[218:221], v[0:3]
	s_setprio 0
	s_barrier
	s_add_i32 s73, 0, 0x18000
	v_add_u32_e32 v148, s73, v149
	s_add_i32 s84, 0, 0x1c000
	ds_read_b128 v[144:147], v148
	ds_read_b128 v[154:157], v148 offset:1024
	ds_read_b128 v[158:161], v148 offset:2048
	ds_read_b128 v[162:165], v148 offset:3072
	v_add_u32_e32 v148, s84, v149
	ds_read_b128 v[166:169], v148
	ds_read_b128 v[170:173], v148 offset:1024
	ds_read_b128 v[174:177], v148 offset:2048
	ds_read_b128 v[178:181], v148 offset:3072
	s_add_u32 s12, s60, 0x80000
	s_addc_u32 s13, s61, 0
	s_mov_b32 m0, s64
	v_lshl_add_u64 v[230:231], s[12:13], 0, v[130:131]
	ds_read_b128 v[182:185], v152 offset:32768
	ds_read_b128 v[186:189], v152 offset:33792
	ds_read_b128 v[190:193], v152 offset:34816
	ds_read_b128 v[202:205], v152 offset:35840
	ds_read_b128 v[206:209], v152 offset:36864
	ds_read_b128 v[210:213], v152 offset:37888
	ds_read_b128 v[214:217], v152 offset:38912
	ds_read_b128 v[218:221], v152 offset:39936
	global_load_lds_dwordx4 v[230:231], off
	v_lshl_add_u64 v[230:231], s[12:13], 0, v[134:135]
	s_mov_b32 m0, s65
	s_nop 0
	global_load_lds_dwordx4 v[230:231], off
	s_waitcnt vmcnt(8)
	s_waitcnt lgkmcnt(0)
	s_barrier
	s_setprio 1
	s_waitcnt lgkmcnt(0)
	v_mfma_f32_16x16x32_bf16 v[126:129], v[144:147], v[182:185], v[126:129]
	v_mfma_f32_16x16x32_bf16 v[122:125], v[158:161], v[182:185], v[122:125]
	v_mfma_f32_16x16x32_bf16 v[110:113], v[144:147], v[190:193], v[110:113]
	v_mfma_f32_16x16x32_bf16 v[106:109], v[158:161], v[190:193], v[106:109]
	v_mfma_f32_16x16x32_bf16 v[92:95], v[144:147], v[206:209], v[92:95]
	v_mfma_f32_16x16x32_bf16 v[88:91], v[158:161], v[206:209], v[88:91]
	v_mfma_f32_16x16x32_bf16 v[76:79], v[144:147], v[214:217], v[76:79]
	v_mfma_f32_16x16x32_bf16 v[72:75], v[158:161], v[214:217], v[72:75]
	v_mfma_f32_16x16x32_bf16 v[126:129], v[154:157], v[186:189], v[126:129]
	v_mfma_f32_16x16x32_bf16 v[122:125], v[162:165], v[186:189], v[122:125]
	v_mfma_f32_16x16x32_bf16 v[110:113], v[154:157], v[202:205], v[110:113]
	v_mfma_f32_16x16x32_bf16 v[106:109], v[162:165], v[202:205], v[106:109]
	v_mfma_f32_16x16x32_bf16 v[92:95], v[154:157], v[210:213], v[92:95]
	v_mfma_f32_16x16x32_bf16 v[88:91], v[162:165], v[210:213], v[88:91]
	v_mfma_f32_16x16x32_bf16 v[76:79], v[154:157], v[218:221], v[76:79]
	v_mfma_f32_16x16x32_bf16 v[72:75], v[162:165], v[218:221], v[72:75]
	s_setprio 0
	s_setprio 1
	v_mfma_f32_16x16x32_bf16 v[118:121], v[166:169], v[182:185], v[118:121]
	v_mfma_f32_16x16x32_bf16 v[114:117], v[174:177], v[182:185], v[114:117]
	v_mfma_f32_16x16x32_bf16 v[102:105], v[166:169], v[190:193], v[102:105]
	v_mfma_f32_16x16x32_bf16 v[98:101], v[174:177], v[190:193], v[98:101]
	v_mfma_f32_16x16x32_bf16 v[84:87], v[166:169], v[206:209], v[84:87]
	v_mfma_f32_16x16x32_bf16 v[80:83], v[174:177], v[206:209], v[80:83]
	v_mfma_f32_16x16x32_bf16 v[68:71], v[166:169], v[214:217], v[68:71]
	v_mfma_f32_16x16x32_bf16 v[64:67], v[174:177], v[214:217], v[64:67]
	v_mfma_f32_16x16x32_bf16 v[118:121], v[170:173], v[186:189], v[118:121]
	v_mfma_f32_16x16x32_bf16 v[114:117], v[178:181], v[186:189], v[114:117]
	v_mfma_f32_16x16x32_bf16 v[102:105], v[170:173], v[202:205], v[102:105]
	v_mfma_f32_16x16x32_bf16 v[98:101], v[178:181], v[202:205], v[98:101]
	v_mfma_f32_16x16x32_bf16 v[84:87], v[170:173], v[210:213], v[84:87]
	v_mfma_f32_16x16x32_bf16 v[80:83], v[178:181], v[210:213], v[80:83]
	v_mfma_f32_16x16x32_bf16 v[68:71], v[170:173], v[218:221], v[68:71]
	v_mfma_f32_16x16x32_bf16 v[64:67], v[178:181], v[218:221], v[64:67]
	s_setprio 0
	s_barrier
; #define PG8_STAGE(bufoff, gbase, voff) do { _Pragma("unroll") for (int _i = 0; _i < 2; ++_i) \
;         __builtin_amdgcn_global_load_lds((const unsigned*)((const char*)(gbase) + (voff)[_i]), (PG8_LAS unsigned*)(lds + (bufoff) + ldsw + _i * 8192), 16, 0, 0); } while (0)
; #define PG8_LDA(dst, b, h) do { _Pragma("unroll") for (int m = 0; m < 4; ++m) _Pragma("unroll") for (int k = 0; k < 2; ++k) dst[m][k] = *(const PG8_LAS bf16x8*)(lds + PG8_SA(b, h) + aoff + m * 2048 + k * 1024); } while (0)
; #define PG8_MMA(ai, bj, At, Bt) do { __builtin_amdgcn_s_setprio(1); _Pragma("unroll") for (int m = 0; m < 4; ++m) _Pragma("unroll") for (int n = 0; n < 2; ++n) _Pragma("unroll") for (int k = 0; k < 2; ++k) \
;         acc[ai][bj][m][n] = __builtin_amdgcn_mfma_f32_16x16x32_bf16(Bt[n][k], At[m][k], acc[ai][bj][m][n], 0, 0, 0); __builtin_amdgcn_s_setprio(0); } while (0)
; #define PG8_WAIT_V(n) asm volatile("s_waitcnt vmcnt(" #n ")" ::: "memory")
; #define PG8_WAIT_L(n) asm volatile("s_waitcnt lgkmcnt(" #n ")" ::: "memory")
; #define PG8_BAR __builtin_amdgcn_s_barrier()
; #define PG8_SCHED __builtin_amdgcn_sched_barrier(0)
; template <class Epi, class Sched, bool ALIGN_EPI = false, bool SP2 = false>
; __device__ __forceinline__ void gemm_phase(PG8_LAS unsigned char* lds, const Gemm g, const Sched& S, const Epi& E) {
;     ...
;         for (int t = 0; t < nt; t += 2) {
;     ...
;             PG8_LDA(At, 1, 1); PG8_STAGE(PG8_SB(1, 0), b3, voffB); PG8_STAGE(PG8_SB(1, 1), b3 + hstep, voffB); PG8_STAGE(PG8_SA(1, 0), a3, voffA);
;             PG8_WAIT_V(8); PG8_WAIT_L(0); PG8_BAR; PG8_MMA(1, 0, At, B0); PG8_MMA(1, 1, At, B1); PG8_BAR; PG8_SCHED;
	s_add_i32 s12, s73, s9
	v_lshl_add_u64 v[222:223], v[222:223], 0, s[36:37]
	s_mov_b32 m0, s12
	ds_read_b128 v[182:185], v152 offset:49152
	ds_read_b128 v[186:189], v152 offset:50176
	ds_read_b128 v[190:193], v152 offset:51200
	ds_read_b128 v[202:205], v152 offset:52224
	ds_read_b128 v[206:209], v152 offset:53248
	ds_read_b128 v[210:213], v152 offset:54272
	ds_read_b128 v[214:217], v152 offset:55296
	ds_read_b128 v[218:221], v152 offset:56320
	global_load_lds_dwordx4 v[222:223], off
	s_add_i32 m0, s12, 0x2000
	s_add_u32 s12, s58, 0x80080
	v_lshl_add_u64 v[222:223], v[224:225], 0, s[36:37]
	s_addc_u32 s13, s59, 0
	s_add_i32 s58, s84, s9
	global_load_lds_dwordx4 v[222:223], off
	v_lshl_add_u64 v[222:223], s[12:13], 0, v[132:133]
	s_mov_b32 m0, s58
	s_nop 0
	global_load_lds_dwordx4 v[222:223], off
	v_lshl_add_u64 v[222:223], s[12:13], 0, v[136:137]
	s_add_i32 m0, s58, 0x2000
	s_nop 0
	global_load_lds_dwordx4 v[222:223], off
	v_lshl_add_u64 v[222:223], v[226:227], 0, s[36:37]
	s_mov_b32 m0, s70
	s_nop 0
	global_load_lds_dwordx4 v[222:223], off
	v_lshl_add_u64 v[222:223], v[228:229], 0, s[36:37]
	s_mov_b32 m0, s71
	s_nop 0
	global_load_lds_dwordx4 v[222:223], off
	s_waitcnt vmcnt(8)
	s_waitcnt lgkmcnt(0)
	s_barrier
	s_setprio 1
	s_waitcnt lgkmcnt(0)
	v_mfma_f32_16x16x32_bf16 v[60:63], v[144:147], v[182:185], v[60:63]
	v_mfma_f32_16x16x32_bf16 v[56:59], v[158:161], v[182:185], v[56:59]
	v_mfma_f32_16x16x32_bf16 v[44:47], v[144:147], v[190:193], v[44:47]
	v_mfma_f32_16x16x32_bf16 v[40:43], v[158:161], v[190:193], v[40:43]
	v_mfma_f32_16x16x32_bf16 v[28:31], v[144:147], v[206:209], v[28:31]
	v_mfma_f32_16x16x32_bf16 v[24:27], v[158:161], v[206:209], v[24:27]
	v_mfma_f32_16x16x32_bf16 v[12:15], v[144:147], v[214:217], v[12:15]
	v_mfma_f32_16x16x32_bf16 v[8:11], v[158:161], v[214:217], v[8:11]
	v_mfma_f32_16x16x32_bf16 v[60:63], v[154:157], v[186:189], v[60:63]
	v_mfma_f32_16x16x32_bf16 v[56:59], v[162:165], v[186:189], v[56:59]
	v_mfma_f32_16x16x32_bf16 v[44:47], v[154:157], v[202:205], v[44:47]
	v_mfma_f32_16x16x32_bf16 v[40:43], v[162:165], v[202:205], v[40:43]
	v_mfma_f32_16x16x32_bf16 v[28:31], v[154:157], v[210:213], v[28:31]
	v_mfma_f32_16x16x32_bf16 v[24:27], v[162:165], v[210:213], v[24:27]
	v_mfma_f32_16x16x32_bf16 v[12:15], v[154:157], v[218:221], v[12:15]
	v_mfma_f32_16x16x32_bf16 v[8:11], v[162:165], v[218:221], v[8:11]
	s_setprio 0
	s_setprio 1
	v_mfma_f32_16x16x32_bf16 v[52:55], v[166:169], v[182:185], v[52:55]
	v_mfma_f32_16x16x32_bf16 v[48:51], v[174:177], v[182:185], v[48:51]
	v_mfma_f32_16x16x32_bf16 v[36:39], v[166:169], v[190:193], v[36:39]
	v_mfma_f32_16x16x32_bf16 v[32:35], v[174:177], v[190:193], v[32:35]
	v_mfma_f32_16x16x32_bf16 v[20:23], v[166:169], v[206:209], v[20:23]
	v_mfma_f32_16x16x32_bf16 v[16:19], v[174:177], v[206:209], v[16:19]
	v_mfma_f32_16x16x32_bf16 v[4:7], v[166:169], v[214:217], v[4:7]
	v_mfma_f32_16x16x32_bf16 v[0:3], v[174:177], v[214:217], v[0:3]
	v_mfma_f32_16x16x32_bf16 v[52:55], v[170:173], v[186:189], v[52:55]
	v_mfma_f32_16x16x32_bf16 v[48:51], v[178:181], v[186:189], v[48:51]
	v_mfma_f32_16x16x32_bf16 v[36:39], v[170:173], v[202:205], v[36:39]
	v_mfma_f32_16x16x32_bf16 v[32:35], v[178:181], v[202:205], v[32:35]
	v_mfma_f32_16x16x32_bf16 v[20:23], v[170:173], v[210:213], v[20:23]
	v_mfma_f32_16x16x32_bf16 v[16:19], v[178:181], v[210:213], v[16:19]
	v_mfma_f32_16x16x32_bf16 v[4:7], v[170:173], v[218:221], v[4:7]
	v_mfma_f32_16x16x32_bf16 v[0:3], v[178:181], v[218:221], v[0:3]
	s_setprio 0
	s_add_i32 s51, s51, 2
	s_add_u32 s18, s18, 0x100
	s_addc_u32 s19, s19, 0
	s_add_u32 s42, s42, 0x100
	s_addc_u32 s43, s43, 0
	s_barrier
	s_cmp_gt_u32 s51, 29
	s_cbranch_scc0 .LBB0_236
	s_and_b64 vcc, exec, s[0:1]
	s_cbranch_vccz .LBB0_239
	s_barrier

; #define PG8_STAGE(bufoff, gbase, voff) do { _Pragma("unroll") for (int _i = 0; _i < 2; ++_i) \
;         __builtin_amdgcn_global_load_lds((const unsigned*)((const char*)(gbase) + (voff)[_i]), (PG8_LAS unsigned*)(lds + (bufoff) + ldsw + _i * 8192), 16, 0, 0); } while (0)
; #define PG8_LDA(dst, b, h) do { _Pragma("unroll") for (int m = 0; m < 4; ++m) _Pragma("unroll") for (int k = 0; k < 2; ++k) dst[m][k] = *(const PG8_LAS bf16x8*)(lds + PG8_SA(b, h) + aoff + m * 2048 + k * 1024); } while (0)
; #define PG8_LDB(dst, b, h) do { _Pragma("unroll") for (int n = 0; n < 2; ++n) _Pragma("unroll") for (int k = 0; k < 2; ++k) dst[n][k] = *(const PG8_LAS bf16x8*)(lds + PG8_SB(b, h) + boff + n * 2048 + k * 1024); } while (0)
; #define PG8_MMA(ai, bj, At, Bt) do { __builtin_amdgcn_s_setprio(1); _Pragma("unroll") for (int m = 0; m < 4; ++m) _Pragma("unroll") for (int n = 0; n < 2; ++n) _Pragma("unroll") for (int k = 0; k < 2; ++k) \
;         acc[ai][bj][m][n] = __builtin_amdgcn_mfma_f32_16x16x32_bf16(Bt[n][k], At[m][k], acc[ai][bj][m][n], 0, 0, 0); __builtin_amdgcn_s_setprio(0); } while (0)
; #define PG8_WAIT_V(n) asm volatile("s_waitcnt vmcnt(" #n ")" ::: "memory")
; #define PG8_BAR __builtin_amdgcn_s_barrier()
; template <class Epi, class Sched, bool ALIGN_EPI = false, bool SP2 = false>
; __device__ __forceinline__ void gemm_phase(PG8_LAS unsigned char* lds, const Gemm g, const Sched& S, const Epi& E) {
;     ...
;         for (int t = 0; t < nt; t += 2) {
;             const bool last = (t == nt - 2);
;             const char* a1 = cA + (size_t)(t + 1) * kstep;
;             const char* a2 = last ? nA : cA + (size_t)(t + 2) * kstep; const char* b2 = last ? nB : cB + (size_t)(t + 2) * kstep;
;             const char* a3 = a2 + kstep; const char* b3 = b2 + kstep;
;             if (last && has_next) S.a_ready(nxt);
;             if constexpr (SP2) {
;             PG8_LDB(B0, 0, 0); PG8_LDB(B1, 0, 1); PG8_SCHED; PG8_LDA(At, 0, 0); PG8_STAGE(PG8_SA(1, 1), a1 + hstep, voffA);
;             PG8_WAIT_V(8); PG8_WAIT_L(0); PG8_BAR; PG8_MMA(0, 0, At, B0); PG8_MMA(0, 1, At, B1); PG8_BAR; PG8_SCHED;
;             PG8_LDA(At, 0, 1); PG8_STAGE(PG8_SB(0, 0), b2, voffB); PG8_STAGE(PG8_SB(0, 1), b2 + hstep, voffB); PG8_STAGE(PG8_SA(0, 0), a2, voffA);
;             PG8_WAIT_V(8); PG8_WAIT_L(0); PG8_BAR; PG8_MMA(1, 0, At, B0); PG8_MMA(1, 1, At, B1); PG8_BAR; PG8_SCHED;
.LBB0_892:
	s_add_u32 s12, s58, 0xfff80080
	s_addc_u32 s13, s59, -1
	s_add_i32 s84, 0, 0x10000
	s_cmp_eq_u32 s73, 28
	s_cselect_b32 s63, s18, s13
	s_cselect_b32 s62, s19, s12
	s_cselect_b32 s61, s26, s55
	s_cselect_b32 s60, s47, s49
	s_add_i32 s85, 0, 0x14000
	v_add_u32_e32 v130, s84, v247
	v_add_u32_e32 v158, s85, v247
	ds_read_b128 v[114:117], v130
	ds_read_b128 v[118:121], v130 offset:1024
	ds_read_b128 v[126:129], v130 offset:2048
	ds_read_b128 v[130:133], v130 offset:3072
	ds_read_b128 v[138:141], v158
	ds_read_b128 v[142:145], v158 offset:1024
	ds_read_b128 v[146:149], v158 offset:2048
	ds_read_b128 v[158:161], v158 offset:3072
	v_lshl_add_u64 v[214:215], s[58:59], 0, v[212:213]
	s_add_i32 m0, s57, 0xc000
	ds_read_b128 v[162:165], v249
	ds_read_b128 v[166:169], v249 offset:1024
	ds_read_b128 v[170:173], v249 offset:2048
	ds_read_b128 v[174:177], v249 offset:3072
	ds_read_b128 v[178:181], v249 offset:4096
	ds_read_b128 v[182:185], v249 offset:5120
	ds_read_b128 v[186:189], v249 offset:6144
	ds_read_b128 v[190:193], v249 offset:7168
	global_load_lds_dwordx4 v[214:215], off
	v_lshl_add_u64 v[214:215], s[58:59], 0, v[210:211]
	s_add_i32 m0, s57, 0xe000
	s_nop 0
	global_load_lds_dwordx4 v[214:215], off
	s_waitcnt vmcnt(8)
	s_waitcnt lgkmcnt(0)
	s_barrier
	s_setprio 1
	s_waitcnt lgkmcnt(0)
	v_mfma_f32_16x16x32_bf16 v[154:157], v[114:117], v[162:165], v[154:157]
	v_mfma_f32_16x16x32_bf16 v[150:153], v[126:129], v[162:165], v[150:153]
	v_mfma_f32_16x16x32_bf16 v[110:113], v[114:117], v[170:173], v[110:113]
	v_mfma_f32_16x16x32_bf16 v[106:109], v[126:129], v[170:173], v[106:109]
	v_mfma_f32_16x16x32_bf16 v[92:95], v[114:117], v[178:181], v[92:95]
	v_mfma_f32_16x16x32_bf16 v[88:91], v[126:129], v[178:181], v[88:91]
	v_mfma_f32_16x16x32_bf16 v[76:79], v[114:117], v[186:189], v[76:79]
	v_mfma_f32_16x16x32_bf16 v[72:75], v[126:129], v[186:189], v[72:75]
	v_mfma_f32_16x16x32_bf16 v[154:157], v[118:121], v[166:169], v[154:157]
	v_mfma_f32_16x16x32_bf16 v[150:153], v[130:133], v[166:169], v[150:153]
	v_mfma_f32_16x16x32_bf16 v[110:113], v[118:121], v[174:177], v[110:113]
	v_mfma_f32_16x16x32_bf16 v[106:109], v[130:133], v[174:177], v[106:109]
	v_mfma_f32_16x16x32_bf16 v[92:95], v[118:121], v[182:185], v[92:95]
	v_mfma_f32_16x16x32_bf16 v[88:91], v[130:133], v[182:185], v[88:91]
	v_mfma_f32_16x16x32_bf16 v[76:79], v[118:121], v[190:193], v[76:79]
	v_mfma_f32_16x16x32_bf16 v[72:75], v[130:133], v[190:193], v[72:75]
	s_setprio 0
	s_setprio 1
	v_mfma_f32_16x16x32_bf16 v[134:137], v[138:141], v[162:165], v[134:137]
	v_mfma_f32_16x16x32_bf16 v[122:125], v[146:149], v[162:165], v[122:125]
	v_mfma_f32_16x16x32_bf16 v[102:105], v[138:141], v[170:173], v[102:105]
	v_mfma_f32_16x16x32_bf16 v[98:101], v[146:149], v[170:173], v[98:101]
	v_mfma_f32_16x16x32_bf16 v[84:87], v[138:141], v[178:181], v[84:87]
	v_mfma_f32_16x16x32_bf16 v[80:83], v[146:149], v[178:181], v[80:83]
	v_mfma_f32_16x16x32_bf16 v[68:71], v[138:141], v[186:189], v[68:71]
	v_mfma_f32_16x16x32_bf16 v[64:67], v[146:149], v[186:189], v[64:67]
	v_mfma_f32_16x16x32_bf16 v[134:137], v[142:145], v[166:169], v[134:137]
	v_mfma_f32_16x16x32_bf16 v[122:125], v[158:161], v[166:169], v[122:125]
	v_mfma_f32_16x16x32_bf16 v[102:105], v[142:145], v[174:177], v[102:105]
	v_mfma_f32_16x16x32_bf16 v[98:101], v[158:161], v[174:177], v[98:101]
	v_mfma_f32_16x16x32_bf16 v[84:87], v[142:145], v[182:185], v[84:87]
	v_mfma_f32_16x16x32_bf16 v[80:83], v[158:161], v[182:185], v[80:83]
	v_mfma_f32_16x16x32_bf16 v[68:71], v[142:145], v[190:193], v[68:71]
	v_mfma_f32_16x16x32_bf16 v[64:67], v[158:161], v[190:193], v[64:67]
	s_setprio 0
	s_barrier
	s_add_i32 s12, s84, s11
	v_lshl_add_u64 v[214:215], s[60:61], 0, v[204:205]
	s_mov_b32 m0, s12
	ds_read_b128 v[162:165], v249 offset:16384
	ds_read_b128 v[166:169], v249 offset:17408
	ds_read_b128 v[170:173], v249 offset:18432
	ds_read_b128 v[174:177], v249 offset:19456
	ds_read_b128 v[178:181], v249 offset:20480
	ds_read_b128 v[182:185], v249 offset:21504
	ds_read_b128 v[186:189], v249 offset:22528
	ds_read_b128 v[190:193], v249 offset:23552
	global_load_lds_dwordx4 v[214:215], off
	s_add_i32 m0, s12, 0x2000
	s_add_u32 s12, s60, 0x80000
	v_lshl_add_u64 v[216:217], s[60:61], 0, v[208:209]
	s_addc_u32 s13, s61, 0
	s_add_i32 s84, s85, s11
	global_load_lds_dwordx4 v[216:217], off
	v_lshl_add_u64 v[218:219], s[12:13], 0, v[204:205]
	s_mov_b32 m0, s84
	v_lshl_add_u64 v[220:221], s[62:63], 0, v[206:207]
	global_load_lds_dwordx4 v[218:219], off
	v_lshl_add_u64 v[218:219], s[12:13], 0, v[208:209]
	s_add_i32 m0, s84, 0x2000
	s_nop 0
	global_load_lds_dwordx4 v[218:219], off
	v_lshl_add_u64 v[218:219], s[62:63], 0, v[202:203]
	s_mov_b32 m0, s57
	s_nop 0
	global_load_lds_dwordx4 v[218:219], off
	s_mov_b32 m0, s65
	s_nop 0
	global_load_lds_dwordx4 v[220:221], off
	s_waitcnt vmcnt(8)
	s_waitcnt lgkmcnt(0)
	s_barrier
; #define PG8_STAGE(bufoff, gbase, voff) do { _Pragma("unroll") for (int _i = 0; _i < 2; ++_i) \
;         __builtin_amdgcn_global_load_lds((const unsigned*)((const char*)(gbase) + (voff)[_i]), (PG8_LAS unsigned*)(lds + (bufoff) + ldsw + _i * 8192), 16, 0, 0); } while (0)
; #define PG8_LDA(dst, b, h) do { _Pragma("unroll") for (int m = 0; m < 4; ++m) _Pragma("unroll") for (int k = 0; k < 2; ++k) dst[m][k] = *(const PG8_LAS bf16x8*)(lds + PG8_SA(b, h) + aoff + m * 2048 + k * 1024); } while (0)
; #define PG8_LDB(dst, b, h) do { _Pragma("unroll") for (int n = 0; n < 2; ++n) _Pragma("unroll") for (int k = 0; k < 2; ++k) dst[n][k] = *(const PG8_LAS bf16x8*)(lds + PG8_SB(b, h) + boff + n * 2048 + k * 1024); } while (0)
; #define PG8_MMA(ai, bj, At, Bt) do { __builtin_amdgcn_s_setprio(1); _Pragma("unroll") for (int m = 0; m < 4; ++m) _Pragma("unroll") for (int n = 0; n < 2; ++n) _Pragma("unroll") for (int k = 0; k < 2; ++k) \
;         acc[ai][bj][m][n] = __builtin_amdgcn_mfma_f32_16x16x32_bf16(Bt[n][k], At[m][k], acc[ai][bj][m][n], 0, 0, 0); __builtin_amdgcn_s_setprio(0); } while (0)
; #define PG8_WAIT_V(n) asm volatile("s_waitcnt vmcnt(" #n ")" ::: "memory")
; #define PG8_WAIT_L(n) asm volatile("s_waitcnt lgkmcnt(" #n ")" ::: "memory")
; #define PG8_BAR __builtin_amdgcn_s_barrier()
; #define PG8_SCHED __builtin_amdgcn_sched_barrier(0)
; template <class Epi, class Sched, bool ALIGN_EPI = false, bool SP2 = false>
; __device__ __forceinline__ void gemm_phase(PG8_LAS unsigned char* lds, const Gemm g, const Sched& S, const Epi& E) {
;     ...
;             PG8_WAIT_V(8); PG8_WAIT_L(0); PG8_BAR; PG8_MMA(1, 0, At, B0); PG8_MMA(1, 1, At, B1); PG8_BAR; PG8_SCHED;
;             PG8_LDB(B0, 1, 0); PG8_LDB(B1, 1, 1); PG8_SCHED; PG8_LDA(At, 1, 0); PG8_STAGE(PG8_SA(0, 1), a2 + hstep, voffA);
;             PG8_WAIT_V(8); PG8_WAIT_L(0); PG8_BAR; PG8_MMA(0, 0, At, B0); PG8_MMA(0, 1, At, B1); PG8_BAR; PG8_SCHED;
	s_setprio 1
	s_waitcnt lgkmcnt(0)
	v_mfma_f32_16x16x32_bf16 v[60:63], v[114:117], v[162:165], v[60:63]
	v_mfma_f32_16x16x32_bf16 v[56:59], v[126:129], v[162:165], v[56:59]
	v_mfma_f32_16x16x32_bf16 v[44:47], v[114:117], v[170:173], v[44:47]
	v_mfma_f32_16x16x32_bf16 v[40:43], v[126:129], v[170:173], v[40:43]
	v_mfma_f32_16x16x32_bf16 v[28:31], v[114:117], v[178:181], v[28:31]
	v_mfma_f32_16x16x32_bf16 v[24:27], v[126:129], v[178:181], v[24:27]
	v_mfma_f32_16x16x32_bf16 v[12:15], v[114:117], v[186:189], v[12:15]
	v_mfma_f32_16x16x32_bf16 v[8:11], v[126:129], v[186:189], v[8:11]
	v_mfma_f32_16x16x32_bf16 v[60:63], v[118:121], v[166:169], v[60:63]
	v_mfma_f32_16x16x32_bf16 v[56:59], v[130:133], v[166:169], v[56:59]
	v_mfma_f32_16x16x32_bf16 v[44:47], v[118:121], v[174:177], v[44:47]
	v_mfma_f32_16x16x32_bf16 v[40:43], v[130:133], v[174:177], v[40:43]
	v_mfma_f32_16x16x32_bf16 v[28:31], v[118:121], v[182:185], v[28:31]
	v_mfma_f32_16x16x32_bf16 v[24:27], v[130:133], v[182:185], v[24:27]
	v_mfma_f32_16x16x32_bf16 v[12:15], v[118:121], v[190:193], v[12:15]
	v_mfma_f32_16x16x32_bf16 v[8:11], v[130:133], v[190:193], v[8:11]
	s_setprio 0
	s_setprio 1
	v_mfma_f32_16x16x32_bf16 v[52:55], v[138:141], v[162:165], v[52:55]
	v_mfma_f32_16x16x32_bf16 v[48:51], v[146:149], v[162:165], v[48:51]
	v_mfma_f32_16x16x32_bf16 v[36:39], v[138:141], v[170:173], v[36:39]
	v_mfma_f32_16x16x32_bf16 v[32:35], v[146:149], v[170:173], v[32:35]
	v_mfma_f32_16x16x32_bf16 v[20:23], v[138:141], v[178:181], v[20:23]
	v_mfma_f32_16x16x32_bf16 v[16:19], v[146:149], v[178:181], v[16:19]
	v_mfma_f32_16x16x32_bf16 v[4:7], v[138:141], v[186:189], v[4:7]
	v_mfma_f32_16x16x32_bf16 v[0:3], v[146:149], v[186:189], v[0:3]
	v_mfma_f32_16x16x32_bf16 v[52:55], v[142:145], v[166:169], v[52:55]
	v_mfma_f32_16x16x32_bf16 v[48:51], v[158:161], v[166:169], v[48:51]
	v_mfma_f32_16x16x32_bf16 v[36:39], v[142:145], v[174:177], v[36:39]
	v_mfma_f32_16x16x32_bf16 v[32:35], v[158:161], v[174:177], v[32:35]
	v_mfma_f32_16x16x32_bf16 v[20:23], v[142:145], v[182:185], v[20:23]
	v_mfma_f32_16x16x32_bf16 v[16:19], v[158:161], v[182:185], v[16:19]
	v_mfma_f32_16x16x32_bf16 v[4:7], v[142:145], v[190:193], v[4:7]
	v_mfma_f32_16x16x32_bf16 v[0:3], v[158:161], v[190:193], v[0:3]
	s_setprio 0
	s_barrier
	s_add_i32 s84, 0, 0x18000
	s_add_i32 s85, 0, 0x1c000
	v_add_u32_e32 v130, s84, v247
	v_add_u32_e32 v158, s85, v247
	ds_read_b128 v[114:117], v130
	ds_read_b128 v[118:121], v130 offset:1024
	ds_read_b128 v[126:129], v130 offset:2048
	ds_read_b128 v[130:133], v130 offset:3072
	ds_read_b128 v[138:141], v158
	ds_read_b128 v[142:145], v158 offset:1024
	ds_read_b128 v[146:149], v158 offset:2048
	ds_read_b128 v[158:161], v158 offset:3072
	s_add_u32 s12, s62, 0x80000
	s_addc_u32 s13, s63, 0
	s_mov_b32 m0, s66
	v_lshl_add_u64 v[222:223], s[12:13], 0, v[202:203]
	ds_read_b128 v[162:165], v249 offset:32768
	ds_read_b128 v[166:169], v249 offset:33792
	ds_read_b128 v[170:173], v249 offset:34816
	ds_read_b128 v[174:177], v249 offset:35840
	ds_read_b128 v[178:181], v249 offset:36864
	ds_read_b128 v[182:185], v249 offset:37888
	ds_read_b128 v[186:189], v249 offset:38912
	ds_read_b128 v[190:193], v249 offset:39936
	global_load_lds_dwordx4 v[222:223], off
	v_lshl_add_u64 v[222:223], s[12:13], 0, v[206:207]
	s_mov_b32 m0, s67
	s_nop 0
	global_load_lds_dwordx4 v[222:223], off
	s_waitcnt vmcnt(8)
	s_waitcnt lgkmcnt(0)
	s_barrier
	s_setprio 1
	s_waitcnt lgkmcnt(0)
	v_mfma_f32_16x16x32_bf16 v[154:157], v[114:117], v[162:165], v[154:157]
	v_mfma_f32_16x16x32_bf16 v[150:153], v[126:129], v[162:165], v[150:153]
	v_mfma_f32_16x16x32_bf16 v[110:113], v[114:117], v[170:173], v[110:113]
	v_mfma_f32_16x16x32_bf16 v[106:109], v[126:129], v[170:173], v[106:109]
	v_mfma_f32_16x16x32_bf16 v[92:95], v[114:117], v[178:181], v[92:95]
	v_mfma_f32_16x16x32_bf16 v[88:91], v[126:129], v[178:181], v[88:91]
	v_mfma_f32_16x16x32_bf16 v[76:79], v[114:117], v[186:189], v[76:79]
	v_mfma_f32_16x16x32_bf16 v[72:75], v[126:129], v[186:189], v[72:75]
	v_mfma_f32_16x16x32_bf16 v[154:157], v[118:121], v[166:169], v[154:157]
	v_mfma_f32_16x16x32_bf16 v[150:153], v[130:133], v[166:169], v[150:153]
	v_mfma_f32_16x16x32_bf16 v[110:113], v[118:121], v[174:177], v[110:113]
	v_mfma_f32_16x16x32_bf16 v[106:109], v[130:133], v[174:177], v[106:109]
	v_mfma_f32_16x16x32_bf16 v[92:95], v[118:121], v[182:185], v[92:95]
	v_mfma_f32_16x16x32_bf16 v[88:91], v[130:133], v[182:185], v[88:91]
	v_mfma_f32_16x16x32_bf16 v[76:79], v[118:121], v[190:193], v[76:79]
	v_mfma_f32_16x16x32_bf16 v[72:75], v[130:133], v[190:193], v[72:75]
	s_setprio 0
	s_setprio 1
	v_mfma_f32_16x16x32_bf16 v[134:137], v[138:141], v[162:165], v[134:137]
	v_mfma_f32_16x16x32_bf16 v[122:125], v[146:149], v[162:165], v[122:125]
	v_mfma_f32_16x16x32_bf16 v[102:105], v[138:141], v[170:173], v[102:105]
	v_mfma_f32_16x16x32_bf16 v[98:101], v[146:149], v[170:173], v[98:101]
	v_mfma_f32_16x16x32_bf16 v[84:87], v[138:141], v[178:181], v[84:87]
	v_mfma_f32_16x16x32_bf16 v[80:83], v[146:149], v[178:181], v[80:83]
	v_mfma_f32_16x16x32_bf16 v[68:71], v[138:141], v[186:189], v[68:71]
	v_mfma_f32_16x16x32_bf16 v[64:67], v[146:149], v[186:189], v[64:67]
	v_mfma_f32_16x16x32_bf16 v[134:137], v[142:145], v[166:169], v[134:137]
	v_mfma_f32_16x16x32_bf16 v[122:125], v[158:161], v[166:169], v[122:125]
	v_mfma_f32_16x16x32_bf16 v[102:105], v[142:145], v[174:177], v[102:105]
	v_mfma_f32_16x16x32_bf16 v[98:101], v[158:161], v[174:177], v[98:101]
	v_mfma_f32_16x16x32_bf16 v[84:87], v[142:145], v[182:185], v[84:87]
	v_mfma_f32_16x16x32_bf16 v[80:83], v[158:161], v[182:185], v[80:83]
	v_mfma_f32_16x16x32_bf16 v[68:71], v[142:145], v[190:193], v[68:71]
	v_mfma_f32_16x16x32_bf16 v[64:67], v[158:161], v[190:193], v[64:67]
	s_setprio 0
	s_barrier
; #define PG8_STAGE(bufoff, gbase, voff) do { _Pragma("unroll") for (int _i = 0; _i < 2; ++_i) \
;         __builtin_amdgcn_global_load_lds((const unsigned*)((const char*)(gbase) + (voff)[_i]), (PG8_LAS unsigned*)(lds + (bufoff) + ldsw + _i * 8192), 16, 0, 0); } while (0)
; #define PG8_LDA(dst, b, h) do { _Pragma("unroll") for (int m = 0; m < 4; ++m) _Pragma("unroll") for (int k = 0; k < 2; ++k) dst[m][k] = *(const PG8_LAS bf16x8*)(lds + PG8_SA(b, h) + aoff + m * 2048 + k * 1024); } while (0)
; #define PG8_MMA(ai, bj, At, Bt) do { __builtin_amdgcn_s_setprio(1); _Pragma("unroll") for (int m = 0; m < 4; ++m) _Pragma("unroll") for (int n = 0; n < 2; ++n) _Pragma("unroll") for (int k = 0; k < 2; ++k) \
;         acc[ai][bj][m][n] = __builtin_amdgcn_mfma_f32_16x16x32_bf16(Bt[n][k], At[m][k], acc[ai][bj][m][n], 0, 0, 0); __builtin_amdgcn_s_setprio(0); } while (0)
; #define PG8_WAIT_V(n) asm volatile("s_waitcnt vmcnt(" #n ")" ::: "memory")
; #define PG8_WAIT_L(n) asm volatile("s_waitcnt lgkmcnt(" #n ")" ::: "memory")
; #define PG8_BAR __builtin_amdgcn_s_barrier()
; #define PG8_SCHED __builtin_amdgcn_sched_barrier(0)
; template <class Epi, class Sched, bool ALIGN_EPI = false, bool SP2 = false>
; __device__ __forceinline__ void gemm_phase(PG8_LAS unsigned char* lds, const Gemm g, const Sched& S, const Epi& E) {
;     ...
;         for (int t = 0; t < nt; t += 2) {
;             const bool last = (t == nt - 2);
;     ...
;             PG8_LDA(At, 1, 1); PG8_STAGE(PG8_SB(1, 0), b3, voffB); PG8_STAGE(PG8_SB(1, 1), b3 + hstep, voffB); PG8_STAGE(PG8_SA(1, 0), a3, voffA);
;             PG8_WAIT_V(8); PG8_WAIT_L(0); PG8_BAR; PG8_MMA(1, 0, At, B0); PG8_MMA(1, 1, At, B1); PG8_BAR; PG8_SCHED;
	s_add_i32 s12, s84, s11
	v_lshl_add_u64 v[214:215], v[214:215], 0, s[36:37]
	s_mov_b32 m0, s12
	ds_read_b128 v[162:165], v249 offset:49152
	ds_read_b128 v[166:169], v249 offset:50176
	ds_read_b128 v[170:173], v249 offset:51200
	ds_read_b128 v[174:177], v249 offset:52224
	ds_read_b128 v[178:181], v249 offset:53248
	ds_read_b128 v[182:185], v249 offset:54272
	ds_read_b128 v[186:189], v249 offset:55296
	ds_read_b128 v[190:193], v249 offset:56320
	global_load_lds_dwordx4 v[214:215], off
	s_add_i32 m0, s12, 0x2000
	s_add_u32 s12, s60, 0x80080
	v_lshl_add_u64 v[214:215], v[216:217], 0, s[36:37]
	s_addc_u32 s13, s61, 0
	s_add_i32 s60, s85, s11
	global_load_lds_dwordx4 v[214:215], off
	v_lshl_add_u64 v[214:215], s[12:13], 0, v[204:205]
	s_mov_b32 m0, s60
	s_nop 0
	global_load_lds_dwordx4 v[214:215], off
	v_lshl_add_u64 v[214:215], s[12:13], 0, v[208:209]
	s_add_i32 m0, s60, 0x2000
	s_nop 0
	global_load_lds_dwordx4 v[214:215], off
	v_lshl_add_u64 v[214:215], v[218:219], 0, s[36:37]
	s_mov_b32 m0, s69
	s_nop 0
	global_load_lds_dwordx4 v[214:215], off
	v_lshl_add_u64 v[214:215], v[220:221], 0, s[36:37]
	s_mov_b32 m0, s70
	s_nop 0
	global_load_lds_dwordx4 v[214:215], off
	s_waitcnt vmcnt(8)
	s_waitcnt lgkmcnt(0)
	s_barrier
	s_setprio 1
	s_waitcnt lgkmcnt(0)
	v_mfma_f32_16x16x32_bf16 v[60:63], v[114:117], v[162:165], v[60:63]
	v_mfma_f32_16x16x32_bf16 v[56:59], v[126:129], v[162:165], v[56:59]
	v_mfma_f32_16x16x32_bf16 v[44:47], v[114:117], v[170:173], v[44:47]
	v_mfma_f32_16x16x32_bf16 v[40:43], v[126:129], v[170:173], v[40:43]
	v_mfma_f32_16x16x32_bf16 v[28:31], v[114:117], v[178:181], v[28:31]
	v_mfma_f32_16x16x32_bf16 v[24:27], v[126:129], v[178:181], v[24:27]
	v_mfma_f32_16x16x32_bf16 v[12:15], v[114:117], v[186:189], v[12:15]
	v_mfma_f32_16x16x32_bf16 v[8:11], v[126:129], v[186:189], v[8:11]
	v_mfma_f32_16x16x32_bf16 v[60:63], v[118:121], v[166:169], v[60:63]
	v_mfma_f32_16x16x32_bf16 v[56:59], v[130:133], v[166:169], v[56:59]
	v_mfma_f32_16x16x32_bf16 v[44:47], v[118:121], v[174:177], v[44:47]
	v_mfma_f32_16x16x32_bf16 v[40:43], v[130:133], v[174:177], v[40:43]
	v_mfma_f32_16x16x32_bf16 v[28:31], v[118:121], v[182:185], v[28:31]
	v_mfma_f32_16x16x32_bf16 v[24:27], v[130:133], v[182:185], v[24:27]
	v_mfma_f32_16x16x32_bf16 v[12:15], v[118:121], v[190:193], v[12:15]
	v_mfma_f32_16x16x32_bf16 v[8:11], v[130:133], v[190:193], v[8:11]
	s_setprio 0
	s_setprio 1
	v_mfma_f32_16x16x32_bf16 v[52:55], v[138:141], v[162:165], v[52:55]
	v_mfma_f32_16x16x32_bf16 v[48:51], v[146:149], v[162:165], v[48:51]
	v_mfma_f32_16x16x32_bf16 v[36:39], v[138:141], v[170:173], v[36:39]
	v_mfma_f32_16x16x32_bf16 v[32:35], v[146:149], v[170:173], v[32:35]
	v_mfma_f32_16x16x32_bf16 v[20:23], v[138:141], v[178:181], v[20:23]
	v_mfma_f32_16x16x32_bf16 v[16:19], v[146:149], v[178:181], v[16:19]
	v_mfma_f32_16x16x32_bf16 v[4:7], v[138:141], v[186:189], v[4:7]
	v_mfma_f32_16x16x32_bf16 v[0:3], v[146:149], v[186:189], v[0:3]
	v_mfma_f32_16x16x32_bf16 v[52:55], v[142:145], v[166:169], v[52:55]
	v_mfma_f32_16x16x32_bf16 v[48:51], v[158:161], v[166:169], v[48:51]
	v_mfma_f32_16x16x32_bf16 v[36:39], v[142:145], v[174:177], v[36:39]
	v_mfma_f32_16x16x32_bf16 v[32:35], v[158:161], v[174:177], v[32:35]
	v_mfma_f32_16x16x32_bf16 v[20:23], v[142:145], v[182:185], v[20:23]
	v_mfma_f32_16x16x32_bf16 v[16:19], v[158:161], v[182:185], v[16:19]
	v_mfma_f32_16x16x32_bf16 v[4:7], v[142:145], v[190:193], v[4:7]
	v_mfma_f32_16x16x32_bf16 v[0:3], v[158:161], v[190:193], v[0:3]
	s_setprio 0
	s_add_i32 s73, s73, 2
	s_add_u32 s49, s49, 0x100
	s_addc_u32 s55, s55, 0
	s_add_u32 s58, s58, 0x100
	s_addc_u32 s59, s59, 0
	s_barrier
	s_cmp_gt_u32 s73, 29
	s_cbranch_scc0 .LBB0_892
	s_and_b64 vcc, exec, s[14:15]
	s_cbranch_vccz .LBB0_895
	s_barrier

; #define PG8_STAGE(bufoff, gbase, voff) do { _Pragma("unroll") for (int _i = 0; _i < 2; ++_i) \
;         __builtin_amdgcn_global_load_lds((const unsigned*)((const char*)(gbase) + (voff)[_i]), (PG8_LAS unsigned*)(lds + (bufoff) + ldsw + _i * 8192), 16, 0, 0); } while (0)
; #define PG8_LDA(dst, b, h) do { _Pragma("unroll") for (int m = 0; m < 4; ++m) _Pragma("unroll") for (int k = 0; k < 2; ++k) dst[m][k] = *(const PG8_LAS bf16x8*)(lds + PG8_SA(b, h) + aoff + m * 2048 + k * 1024); } while (0)
; #define PG8_LDB(dst, b, h) do { _Pragma("unroll") for (int n = 0; n < 2; ++n) _Pragma("unroll") for (int k = 0; k < 2; ++k) dst[n][k] = *(const PG8_LAS bf16x8*)(lds + PG8_SB(b, h) + boff + n * 2048 + k * 1024); } while (0)
; #define PG8_MMA(ai, bj, At, Bt) do { __builtin_amdgcn_s_setprio(1); _Pragma("unroll") for (int m = 0; m < 4; ++m) _Pragma("unroll") for (int n = 0; n < 2; ++n) _Pragma("unroll") for (int k = 0; k < 2; ++k) \
;         acc[ai][bj][m][n] = __builtin_amdgcn_mfma_f32_16x16x32_bf16(Bt[n][k], At[m][k], acc[ai][bj][m][n], 0, 0, 0); __builtin_amdgcn_s_setprio(0); } while (0)
; #define PG8_WAIT_V(n) asm volatile("s_waitcnt vmcnt(" #n ")" ::: "memory")
; #define PG8_BAR __builtin_amdgcn_s_barrier()
; template <class Epi, class Sched, bool ALIGN_EPI = false, bool SP2 = false>
; __device__ __forceinline__ void gemm_phase(PG8_LAS unsigned char* lds, const Gemm g, const Sched& S, const Epi& E) {
;     ...
;         for (int t = 0; t < nt; t += 2) {
;             const bool last = (t == nt - 2);
;             const char* a1 = cA + (size_t)(t + 1) * kstep;
;             const char* a2 = last ? nA : cA + (size_t)(t + 2) * kstep; const char* b2 = last ? nB : cB + (size_t)(t + 2) * kstep;
;             const char* a3 = a2 + kstep; const char* b3 = b2 + kstep;
;             if (last && has_next) S.a_ready(nxt);
;             if constexpr (SP2) {
;             PG8_LDB(B0, 0, 0); PG8_LDB(B1, 0, 1); PG8_SCHED; PG8_LDA(At, 0, 0); PG8_STAGE(PG8_SA(1, 1), a1 + hstep, voffA);
;             PG8_WAIT_V(8); PG8_WAIT_L(0); PG8_BAR; PG8_MMA(0, 0, At, B0); PG8_MMA(0, 1, At, B1); PG8_BAR; PG8_SCHED;
;             PG8_LDA(At, 0, 1); PG8_STAGE(PG8_SB(0, 0), b2, voffB); PG8_STAGE(PG8_SB(0, 1), b2 + hstep, voffB); PG8_STAGE(PG8_SA(0, 0), a2, voffA);
;             PG8_WAIT_V(8); PG8_WAIT_L(0); PG8_BAR; PG8_MMA(1, 0, At, B0); PG8_MMA(1, 1, At, B1); PG8_BAR; PG8_SCHED;
.LBB0_1016:
	s_add_u32 s12, s14, 0xfff80080
	s_addc_u32 s13, s15, -1
	s_add_i32 s70, 0, 0x10000
	s_cmp_eq_u32 s69, 28
	s_cselect_b32 s59, s1, s13
	s_cselect_b32 s58, s5, s12
	v_add_u32_e32 v148, s70, v149
	s_cselect_b32 s43, s10, s53
	s_cselect_b32 s42, s11, s51
	s_add_i32 s71, 0, 0x14000
	ds_read_b128 v[144:147], v148
	ds_read_b128 v[154:157], v148 offset:1024
	ds_read_b128 v[158:161], v148 offset:2048
	ds_read_b128 v[162:165], v148 offset:3072
	v_add_u32_e32 v148, s71, v149
	ds_read_b128 v[166:169], v148
	ds_read_b128 v[170:173], v148 offset:1024
	ds_read_b128 v[174:177], v148 offset:2048
	ds_read_b128 v[178:181], v148 offset:3072
	v_lshl_add_u64 v[222:223], s[14:15], 0, v[142:143]
	s_add_i32 m0, s61, 0xc000
	ds_read_b128 v[182:185], v152
	ds_read_b128 v[186:189], v152 offset:1024
	ds_read_b128 v[190:193], v152 offset:2048
	ds_read_b128 v[202:205], v152 offset:3072
	ds_read_b128 v[206:209], v152 offset:4096
	ds_read_b128 v[210:213], v152 offset:5120
	ds_read_b128 v[214:217], v152 offset:6144
	ds_read_b128 v[218:221], v152 offset:7168
	global_load_lds_dwordx4 v[222:223], off
	v_lshl_add_u64 v[222:223], s[14:15], 0, v[140:141]
	s_add_i32 m0, s61, 0xe000
	s_nop 0
	global_load_lds_dwordx4 v[222:223], off
	s_waitcnt vmcnt(8)
	s_waitcnt lgkmcnt(0)
	s_barrier
	s_setprio 1
	s_waitcnt lgkmcnt(0)
	v_mfma_f32_16x16x32_bf16 v[126:129], v[144:147], v[182:185], v[126:129]
	v_mfma_f32_16x16x32_bf16 v[122:125], v[158:161], v[182:185], v[122:125]
	v_mfma_f32_16x16x32_bf16 v[110:113], v[144:147], v[190:193], v[110:113]
	v_mfma_f32_16x16x32_bf16 v[106:109], v[158:161], v[190:193], v[106:109]
	v_mfma_f32_16x16x32_bf16 v[92:95], v[144:147], v[206:209], v[92:95]
	v_mfma_f32_16x16x32_bf16 v[88:91], v[158:161], v[206:209], v[88:91]
	v_mfma_f32_16x16x32_bf16 v[76:79], v[144:147], v[214:217], v[76:79]
	v_mfma_f32_16x16x32_bf16 v[72:75], v[158:161], v[214:217], v[72:75]
	v_mfma_f32_16x16x32_bf16 v[126:129], v[154:157], v[186:189], v[126:129]
	v_mfma_f32_16x16x32_bf16 v[122:125], v[162:165], v[186:189], v[122:125]
	v_mfma_f32_16x16x32_bf16 v[110:113], v[154:157], v[202:205], v[110:113]
	v_mfma_f32_16x16x32_bf16 v[106:109], v[162:165], v[202:205], v[106:109]
	v_mfma_f32_16x16x32_bf16 v[92:95], v[154:157], v[210:213], v[92:95]
	v_mfma_f32_16x16x32_bf16 v[88:91], v[162:165], v[210:213], v[88:91]
	v_mfma_f32_16x16x32_bf16 v[76:79], v[154:157], v[218:221], v[76:79]
	v_mfma_f32_16x16x32_bf16 v[72:75], v[162:165], v[218:221], v[72:75]
	s_setprio 0
	s_setprio 1
	v_mfma_f32_16x16x32_bf16 v[118:121], v[166:169], v[182:185], v[118:121]
	v_mfma_f32_16x16x32_bf16 v[114:117], v[174:177], v[182:185], v[114:117]
	v_mfma_f32_16x16x32_bf16 v[102:105], v[166:169], v[190:193], v[102:105]
	v_mfma_f32_16x16x32_bf16 v[98:101], v[174:177], v[190:193], v[98:101]
	v_mfma_f32_16x16x32_bf16 v[84:87], v[166:169], v[206:209], v[84:87]
	v_mfma_f32_16x16x32_bf16 v[80:83], v[174:177], v[206:209], v[80:83]
	v_mfma_f32_16x16x32_bf16 v[68:71], v[166:169], v[214:217], v[68:71]
	v_mfma_f32_16x16x32_bf16 v[64:67], v[174:177], v[214:217], v[64:67]
	v_mfma_f32_16x16x32_bf16 v[118:121], v[170:173], v[186:189], v[118:121]
	v_mfma_f32_16x16x32_bf16 v[114:117], v[178:181], v[186:189], v[114:117]
	v_mfma_f32_16x16x32_bf16 v[102:105], v[170:173], v[202:205], v[102:105]
	v_mfma_f32_16x16x32_bf16 v[98:101], v[178:181], v[202:205], v[98:101]
	v_mfma_f32_16x16x32_bf16 v[84:87], v[170:173], v[210:213], v[84:87]
	v_mfma_f32_16x16x32_bf16 v[80:83], v[178:181], v[210:213], v[80:83]
	v_mfma_f32_16x16x32_bf16 v[68:71], v[170:173], v[218:221], v[68:71]
	v_mfma_f32_16x16x32_bf16 v[64:67], v[178:181], v[218:221], v[64:67]
	s_setprio 0
	s_barrier
	s_add_i32 s12, s70, s9
	v_lshl_add_u64 v[222:223], s[42:43], 0, v[132:133]
	s_mov_b32 m0, s12
	ds_read_b128 v[182:185], v152 offset:16384
	ds_read_b128 v[186:189], v152 offset:17408
	ds_read_b128 v[190:193], v152 offset:18432
	ds_read_b128 v[202:205], v152 offset:19456
	ds_read_b128 v[206:209], v152 offset:20480
	ds_read_b128 v[210:213], v152 offset:21504
	ds_read_b128 v[214:217], v152 offset:22528
	ds_read_b128 v[218:221], v152 offset:23552
	global_load_lds_dwordx4 v[222:223], off
	s_add_i32 m0, s12, 0x2000
	s_add_u32 s12, s42, 0x80000
	v_lshl_add_u64 v[224:225], s[42:43], 0, v[136:137]
	s_addc_u32 s13, s43, 0
	s_add_i32 s70, s71, s9
	global_load_lds_dwordx4 v[224:225], off
	v_lshl_add_u64 v[226:227], s[12:13], 0, v[132:133]
	s_mov_b32 m0, s70
	v_lshl_add_u64 v[228:229], s[58:59], 0, v[134:135]
	global_load_lds_dwordx4 v[226:227], off
	v_lshl_add_u64 v[226:227], s[12:13], 0, v[136:137]
	s_add_i32 m0, s70, 0x2000
	s_nop 0
	global_load_lds_dwordx4 v[226:227], off
	v_lshl_add_u64 v[226:227], s[58:59], 0, v[130:131]
	s_mov_b32 m0, s61
	s_nop 0
	global_load_lds_dwordx4 v[226:227], off
	s_mov_b32 m0, s62
	s_nop 0
	global_load_lds_dwordx4 v[228:229], off
	s_waitcnt vmcnt(8)
	s_waitcnt lgkmcnt(0)
	s_barrier
; #define PG8_STAGE(bufoff, gbase, voff) do { _Pragma("unroll") for (int _i = 0; _i < 2; ++_i) \
;         __builtin_amdgcn_global_load_lds((const unsigned*)((const char*)(gbase) + (voff)[_i]), (PG8_LAS unsigned*)(lds + (bufoff) + ldsw + _i * 8192), 16, 0, 0); } while (0)
; #define PG8_LDA(dst, b, h) do { _Pragma("unroll") for (int m = 0; m < 4; ++m) _Pragma("unroll") for (int k = 0; k < 2; ++k) dst[m][k] = *(const PG8_LAS bf16x8*)(lds + PG8_SA(b, h) + aoff + m * 2048 + k * 1024); } while (0)
; #define PG8_LDB(dst, b, h) do { _Pragma("unroll") for (int n = 0; n < 2; ++n) _Pragma("unroll") for (int k = 0; k < 2; ++k) dst[n][k] = *(const PG8_LAS bf16x8*)(lds + PG8_SB(b, h) + boff + n * 2048 + k * 1024); } while (0)
; #define PG8_MMA(ai, bj, At, Bt) do { __builtin_amdgcn_s_setprio(1); _Pragma("unroll") for (int m = 0; m < 4; ++m) _Pragma("unroll") for (int n = 0; n < 2; ++n) _Pragma("unroll") for (int k = 0; k < 2; ++k) \
;         acc[ai][bj][m][n] = __builtin_amdgcn_mfma_f32_16x16x32_bf16(Bt[n][k], At[m][k], acc[ai][bj][m][n], 0, 0, 0); __builtin_amdgcn_s_setprio(0); } while (0)
; #define PG8_WAIT_V(n) asm volatile("s_waitcnt vmcnt(" #n ")" ::: "memory")
; #define PG8_WAIT_L(n) asm volatile("s_waitcnt lgkmcnt(" #n ")" ::: "memory")
; #define PG8_BAR __builtin_amdgcn_s_barrier()
; #define PG8_SCHED __builtin_amdgcn_sched_barrier(0)
; template <class Epi, class Sched, bool ALIGN_EPI = false, bool SP2 = false>
; __device__ __forceinline__ void gemm_phase(PG8_LAS unsigned char* lds, const Gemm g, const Sched& S, const Epi& E) {
;     ...
;             PG8_WAIT_V(8); PG8_WAIT_L(0); PG8_BAR; PG8_MMA(1, 0, At, B0); PG8_MMA(1, 1, At, B1); PG8_BAR; PG8_SCHED;
;             PG8_LDB(B0, 1, 0); PG8_LDB(B1, 1, 1); PG8_SCHED; PG8_LDA(At, 1, 0); PG8_STAGE(PG8_SA(0, 1), a2 + hstep, voffA);
;             PG8_WAIT_V(8); PG8_WAIT_L(0); PG8_BAR; PG8_MMA(0, 0, At, B0); PG8_MMA(0, 1, At, B1); PG8_BAR; PG8_SCHED;
	s_setprio 1
	s_waitcnt lgkmcnt(0)
	v_mfma_f32_16x16x32_bf16 v[60:63], v[144:147], v[182:185], v[60:63]
	v_mfma_f32_16x16x32_bf16 v[56:59], v[158:161], v[182:185], v[56:59]
	v_mfma_f32_16x16x32_bf16 v[44:47], v[144:147], v[190:193], v[44:47]
	v_mfma_f32_16x16x32_bf16 v[40:43], v[158:161], v[190:193], v[40:43]
	v_mfma_f32_16x16x32_bf16 v[28:31], v[144:147], v[206:209], v[28:31]
	v_mfma_f32_16x16x32_bf16 v[24:27], v[158:161], v[206:209], v[24:27]
	v_mfma_f32_16x16x32_bf16 v[12:15], v[144:147], v[214:217], v[12:15]
	v_mfma_f32_16x16x32_bf16 v[8:11], v[158:161], v[214:217], v[8:11]
	v_mfma_f32_16x16x32_bf16 v[60:63], v[154:157], v[186:189], v[60:63]
	v_mfma_f32_16x16x32_bf16 v[56:59], v[162:165], v[186:189], v[56:59]
	v_mfma_f32_16x16x32_bf16 v[44:47], v[154:157], v[202:205], v[44:47]
	v_mfma_f32_16x16x32_bf16 v[40:43], v[162:165], v[202:205], v[40:43]
	v_mfma_f32_16x16x32_bf16 v[28:31], v[154:157], v[210:213], v[28:31]
	v_mfma_f32_16x16x32_bf16 v[24:27], v[162:165], v[210:213], v[24:27]
	v_mfma_f32_16x16x32_bf16 v[12:15], v[154:157], v[218:221], v[12:15]
	v_mfma_f32_16x16x32_bf16 v[8:11], v[162:165], v[218:221], v[8:11]
	s_setprio 0
	s_setprio 1
	v_mfma_f32_16x16x32_bf16 v[52:55], v[166:169], v[182:185], v[52:55]
	v_mfma_f32_16x16x32_bf16 v[48:51], v[174:177], v[182:185], v[48:51]
	v_mfma_f32_16x16x32_bf16 v[36:39], v[166:169], v[190:193], v[36:39]
	v_mfma_f32_16x16x32_bf16 v[32:35], v[174:177], v[190:193], v[32:35]
	v_mfma_f32_16x16x32_bf16 v[20:23], v[166:169], v[206:209], v[20:23]
	v_mfma_f32_16x16x32_bf16 v[16:19], v[174:177], v[206:209], v[16:19]
	v_mfma_f32_16x16x32_bf16 v[4:7], v[166:169], v[214:217], v[4:7]
	v_mfma_f32_16x16x32_bf16 v[0:3], v[174:177], v[214:217], v[0:3]
	v_mfma_f32_16x16x32_bf16 v[52:55], v[170:173], v[186:189], v[52:55]
	v_mfma_f32_16x16x32_bf16 v[48:51], v[178:181], v[186:189], v[48:51]
	v_mfma_f32_16x16x32_bf16 v[36:39], v[170:173], v[202:205], v[36:39]
	v_mfma_f32_16x16x32_bf16 v[32:35], v[178:181], v[202:205], v[32:35]
	v_mfma_f32_16x16x32_bf16 v[20:23], v[170:173], v[210:213], v[20:23]
	v_mfma_f32_16x16x32_bf16 v[16:19], v[178:181], v[210:213], v[16:19]
	v_mfma_f32_16x16x32_bf16 v[4:7], v[170:173], v[218:221], v[4:7]
	v_mfma_f32_16x16x32_bf16 v[0:3], v[178:181], v[218:221], v[0:3]
	s_setprio 0
	s_barrier
	s_add_i32 s70, 0, 0x18000
	v_add_u32_e32 v148, s70, v149
	s_add_i32 s71, 0, 0x1c000
	ds_read_b128 v[144:147], v148
	ds_read_b128 v[154:157], v148 offset:1024
	ds_read_b128 v[158:161], v148 offset:2048
	ds_read_b128 v[162:165], v148 offset:3072
	v_add_u32_e32 v148, s71, v149
	ds_read_b128 v[166:169], v148
	ds_read_b128 v[170:173], v148 offset:1024
	ds_read_b128 v[174:177], v148 offset:2048
	ds_read_b128 v[178:181], v148 offset:3072
	s_add_u32 s12, s58, 0x80000
	s_addc_u32 s13, s59, 0
	s_mov_b32 m0, s63
	v_lshl_add_u64 v[230:231], s[12:13], 0, v[130:131]
	ds_read_b128 v[182:185], v152 offset:32768
	ds_read_b128 v[186:189], v152 offset:33792
	ds_read_b128 v[190:193], v152 offset:34816
	ds_read_b128 v[202:205], v152 offset:35840
	ds_read_b128 v[206:209], v152 offset:36864
	ds_read_b128 v[210:213], v152 offset:37888
	ds_read_b128 v[214:217], v152 offset:38912
	ds_read_b128 v[218:221], v152 offset:39936
	global_load_lds_dwordx4 v[230:231], off
	v_lshl_add_u64 v[230:231], s[12:13], 0, v[134:135]
	s_mov_b32 m0, s65
	s_nop 0
	global_load_lds_dwordx4 v[230:231], off
	s_waitcnt vmcnt(8)
	s_waitcnt lgkmcnt(0)
	s_barrier
	s_setprio 1
	s_waitcnt lgkmcnt(0)
	v_mfma_f32_16x16x32_bf16 v[126:129], v[144:147], v[182:185], v[126:129]
	v_mfma_f32_16x16x32_bf16 v[122:125], v[158:161], v[182:185], v[122:125]
	v_mfma_f32_16x16x32_bf16 v[110:113], v[144:147], v[190:193], v[110:113]
	v_mfma_f32_16x16x32_bf16 v[106:109], v[158:161], v[190:193], v[106:109]
	v_mfma_f32_16x16x32_bf16 v[92:95], v[144:147], v[206:209], v[92:95]
	v_mfma_f32_16x16x32_bf16 v[88:91], v[158:161], v[206:209], v[88:91]
	v_mfma_f32_16x16x32_bf16 v[76:79], v[144:147], v[214:217], v[76:79]
	v_mfma_f32_16x16x32_bf16 v[72:75], v[158:161], v[214:217], v[72:75]
	v_mfma_f32_16x16x32_bf16 v[126:129], v[154:157], v[186:189], v[126:129]
	v_mfma_f32_16x16x32_bf16 v[122:125], v[162:165], v[186:189], v[122:125]
	v_mfma_f32_16x16x32_bf16 v[110:113], v[154:157], v[202:205], v[110:113]
	v_mfma_f32_16x16x32_bf16 v[106:109], v[162:165], v[202:205], v[106:109]
	v_mfma_f32_16x16x32_bf16 v[92:95], v[154:157], v[210:213], v[92:95]
	v_mfma_f32_16x16x32_bf16 v[88:91], v[162:165], v[210:213], v[88:91]
	v_mfma_f32_16x16x32_bf16 v[76:79], v[154:157], v[218:221], v[76:79]
	v_mfma_f32_16x16x32_bf16 v[72:75], v[162:165], v[218:221], v[72:75]
	s_setprio 0
	s_setprio 1
	v_mfma_f32_16x16x32_bf16 v[118:121], v[166:169], v[182:185], v[118:121]
	v_mfma_f32_16x16x32_bf16 v[114:117], v[174:177], v[182:185], v[114:117]
	v_mfma_f32_16x16x32_bf16 v[102:105], v[166:169], v[190:193], v[102:105]
	v_mfma_f32_16x16x32_bf16 v[98:101], v[174:177], v[190:193], v[98:101]
	v_mfma_f32_16x16x32_bf16 v[84:87], v[166:169], v[206:209], v[84:87]
	v_mfma_f32_16x16x32_bf16 v[80:83], v[174:177], v[206:209], v[80:83]
	v_mfma_f32_16x16x32_bf16 v[68:71], v[166:169], v[214:217], v[68:71]
	v_mfma_f32_16x16x32_bf16 v[64:67], v[174:177], v[214:217], v[64:67]
	v_mfma_f32_16x16x32_bf16 v[118:121], v[170:173], v[186:189], v[118:121]
	v_mfma_f32_16x16x32_bf16 v[114:117], v[178:181], v[186:189], v[114:117]
	v_mfma_f32_16x16x32_bf16 v[102:105], v[170:173], v[202:205], v[102:105]
	v_mfma_f32_16x16x32_bf16 v[98:101], v[178:181], v[202:205], v[98:101]
	v_mfma_f32_16x16x32_bf16 v[84:87], v[170:173], v[210:213], v[84:87]
	v_mfma_f32_16x16x32_bf16 v[80:83], v[178:181], v[210:213], v[80:83]
	v_mfma_f32_16x16x32_bf16 v[68:71], v[170:173], v[218:221], v[68:71]
	v_mfma_f32_16x16x32_bf16 v[64:67], v[178:181], v[218:221], v[64:67]
	s_setprio 0
	s_barrier
; #define PG8_STAGE(bufoff, gbase, voff) do { _Pragma("unroll") for (int _i = 0; _i < 2; ++_i) \
;         __builtin_amdgcn_global_load_lds((const unsigned*)((const char*)(gbase) + (voff)[_i]), (PG8_LAS unsigned*)(lds + (bufoff) + ldsw + _i * 8192), 16, 0, 0); } while (0)
; #define PG8_LDA(dst, b, h) do { _Pragma("unroll") for (int m = 0; m < 4; ++m) _Pragma("unroll") for (int k = 0; k < 2; ++k) dst[m][k] = *(const PG8_LAS bf16x8*)(lds + PG8_SA(b, h) + aoff + m * 2048 + k * 1024); } while (0)
; #define PG8_MMA(ai, bj, At, Bt) do { __builtin_amdgcn_s_setprio(1); _Pragma("unroll") for (int m = 0; m < 4; ++m) _Pragma("unroll") for (int n = 0; n < 2; ++n) _Pragma("unroll") for (int k = 0; k < 2; ++k) \
;         acc[ai][bj][m][n] = __builtin_amdgcn_mfma_f32_16x16x32_bf16(Bt[n][k], At[m][k], acc[ai][bj][m][n], 0, 0, 0); __builtin_amdgcn_s_setprio(0); } while (0)
; #define PG8_WAIT_V(n) asm volatile("s_waitcnt vmcnt(" #n ")" ::: "memory")
; #define PG8_WAIT_L(n) asm volatile("s_waitcnt lgkmcnt(" #n ")" ::: "memory")
; #define PG8_BAR __builtin_amdgcn_s_barrier()
; #define PG8_SCHED __builtin_amdgcn_sched_barrier(0)
; template <class Epi, class Sched, bool ALIGN_EPI = false, bool SP2 = false>
; __device__ __forceinline__ void gemm_phase(PG8_LAS unsigned char* lds, const Gemm g, const Sched& S, const Epi& E) {
;     ...
;         for (int t = 0; t < nt; t += 2) {
;             const bool last = (t == nt - 2);
;     ...
;             PG8_LDA(At, 1, 1); PG8_STAGE(PG8_SB(1, 0), b3, voffB); PG8_STAGE(PG8_SB(1, 1), b3 + hstep, voffB); PG8_STAGE(PG8_SA(1, 0), a3, voffA);
;             PG8_WAIT_V(8); PG8_WAIT_L(0); PG8_BAR; PG8_MMA(1, 0, At, B0); PG8_MMA(1, 1, At, B1); PG8_BAR; PG8_SCHED;
	s_add_i32 s12, s70, s9
	v_lshl_add_u64 v[222:223], v[222:223], 0, s[36:37]
	s_mov_b32 m0, s12
	ds_read_b128 v[182:185], v152 offset:49152
	ds_read_b128 v[186:189], v152 offset:50176
	ds_read_b128 v[190:193], v152 offset:51200
	ds_read_b128 v[202:205], v152 offset:52224
	ds_read_b128 v[206:209], v152 offset:53248
	ds_read_b128 v[210:213], v152 offset:54272
	ds_read_b128 v[214:217], v152 offset:55296
	ds_read_b128 v[218:221], v152 offset:56320
	global_load_lds_dwordx4 v[222:223], off
	s_add_i32 m0, s12, 0x2000
	s_add_u32 s12, s42, 0x80080
	v_lshl_add_u64 v[222:223], v[224:225], 0, s[36:37]
	s_addc_u32 s13, s43, 0
	s_add_i32 s42, s71, s9
	global_load_lds_dwordx4 v[222:223], off
	v_lshl_add_u64 v[222:223], s[12:13], 0, v[132:133]
	s_mov_b32 m0, s42
	s_nop 0
	global_load_lds_dwordx4 v[222:223], off
	v_lshl_add_u64 v[222:223], s[12:13], 0, v[136:137]
	s_add_i32 m0, s42, 0x2000
	s_nop 0
	global_load_lds_dwordx4 v[222:223], off
	v_lshl_add_u64 v[222:223], v[226:227], 0, s[36:37]
	s_mov_b32 m0, s66
	s_nop 0
	global_load_lds_dwordx4 v[222:223], off
	v_lshl_add_u64 v[222:223], v[228:229], 0, s[36:37]
	s_mov_b32 m0, s67
	s_nop 0
	global_load_lds_dwordx4 v[222:223], off
	s_waitcnt vmcnt(8)
	s_waitcnt lgkmcnt(0)
	s_barrier
	s_setprio 1
	s_waitcnt lgkmcnt(0)
	v_mfma_f32_16x16x32_bf16 v[60:63], v[144:147], v[182:185], v[60:63]
	v_mfma_f32_16x16x32_bf16 v[56:59], v[158:161], v[182:185], v[56:59]
	v_mfma_f32_16x16x32_bf16 v[44:47], v[144:147], v[190:193], v[44:47]
	v_mfma_f32_16x16x32_bf16 v[40:43], v[158:161], v[190:193], v[40:43]
	v_mfma_f32_16x16x32_bf16 v[28:31], v[144:147], v[206:209], v[28:31]
	v_mfma_f32_16x16x32_bf16 v[24:27], v[158:161], v[206:209], v[24:27]
	v_mfma_f32_16x16x32_bf16 v[12:15], v[144:147], v[214:217], v[12:15]
	v_mfma_f32_16x16x32_bf16 v[8:11], v[158:161], v[214:217], v[8:11]
	v_mfma_f32_16x16x32_bf16 v[60:63], v[154:157], v[186:189], v[60:63]
	v_mfma_f32_16x16x32_bf16 v[56:59], v[162:165], v[186:189], v[56:59]
	v_mfma_f32_16x16x32_bf16 v[44:47], v[154:157], v[202:205], v[44:47]
	v_mfma_f32_16x16x32_bf16 v[40:43], v[162:165], v[202:205], v[40:43]
	v_mfma_f32_16x16x32_bf16 v[28:31], v[154:157], v[210:213], v[28:31]
	v_mfma_f32_16x16x32_bf16 v[24:27], v[162:165], v[210:213], v[24:27]
	v_mfma_f32_16x16x32_bf16 v[12:15], v[154:157], v[218:221], v[12:15]
	v_mfma_f32_16x16x32_bf16 v[8:11], v[162:165], v[218:221], v[8:11]
	s_setprio 0
	s_setprio 1
	v_mfma_f32_16x16x32_bf16 v[52:55], v[166:169], v[182:185], v[52:55]
	v_mfma_f32_16x16x32_bf16 v[48:51], v[174:177], v[182:185], v[48:51]
	v_mfma_f32_16x16x32_bf16 v[36:39], v[166:169], v[190:193], v[36:39]
	v_mfma_f32_16x16x32_bf16 v[32:35], v[174:177], v[190:193], v[32:35]
	v_mfma_f32_16x16x32_bf16 v[20:23], v[166:169], v[206:209], v[20:23]
	v_mfma_f32_16x16x32_bf16 v[16:19], v[174:177], v[206:209], v[16:19]
	v_mfma_f32_16x16x32_bf16 v[4:7], v[166:169], v[214:217], v[4:7]
	v_mfma_f32_16x16x32_bf16 v[0:3], v[174:177], v[214:217], v[0:3]
	v_mfma_f32_16x16x32_bf16 v[52:55], v[170:173], v[186:189], v[52:55]
	v_mfma_f32_16x16x32_bf16 v[48:51], v[178:181], v[186:189], v[48:51]
	v_mfma_f32_16x16x32_bf16 v[36:39], v[170:173], v[202:205], v[36:39]
	v_mfma_f32_16x16x32_bf16 v[32:35], v[178:181], v[202:205], v[32:35]
	v_mfma_f32_16x16x32_bf16 v[20:23], v[170:173], v[210:213], v[20:23]
	v_mfma_f32_16x16x32_bf16 v[16:19], v[178:181], v[210:213], v[16:19]
	v_mfma_f32_16x16x32_bf16 v[4:7], v[170:173], v[218:221], v[4:7]
	v_mfma_f32_16x16x32_bf16 v[0:3], v[178:181], v[218:221], v[0:3]
	s_setprio 0
	s_add_i32 s69, s69, 2
	s_add_u32 s51, s51, 0x100
	s_addc_u32 s53, s53, 0
	s_add_u32 s14, s14, 0x100
	s_addc_u32 s15, s15, 0
	s_barrier
	s_cmp_gt_u32 s69, 29
	s_cbranch_scc0 .LBB0_1016
	s_and_b64 vcc, exec, s[48:49]
	s_cbranch_vccz .LBB0_1019
	s_barrier

; #define PG8_STAGE(bufoff, gbase, voff) do { _Pragma("unroll") for (int _i = 0; _i < 2; ++_i) \
;         __builtin_amdgcn_global_load_lds((const unsigned*)((const char*)(gbase) + (voff)[_i]), (PG8_LAS unsigned*)(lds + (bufoff) + ldsw + _i * 8192), 16, 0, 0); } while (0)
; #define PG8_LDA(dst, b, h) do { _Pragma("unroll") for (int m = 0; m < 4; ++m) _Pragma("unroll") for (int k = 0; k < 2; ++k) dst[m][k] = *(const PG8_LAS bf16x8*)(lds + PG8_SA(b, h) + aoff + m * 2048 + k * 1024); } while (0)
; #define PG8_LDB(dst, b, h) do { _Pragma("unroll") for (int n = 0; n < 2; ++n) _Pragma("unroll") for (int k = 0; k < 2; ++k) dst[n][k] = *(const PG8_LAS bf16x8*)(lds + PG8_SB(b, h) + boff + n * 2048 + k * 1024); } while (0)
; #define PG8_MMA(ai, bj, At, Bt) do { __builtin_amdgcn_s_setprio(1); _Pragma("unroll") for (int m = 0; m < 4; ++m) _Pragma("unroll") for (int n = 0; n < 2; ++n) _Pragma("unroll") for (int k = 0; k < 2; ++k) \
;         acc[ai][bj][m][n] = __builtin_amdgcn_mfma_f32_16x16x32_bf16(Bt[n][k], At[m][k], acc[ai][bj][m][n], 0, 0, 0); __builtin_amdgcn_s_setprio(0); } while (0)
; #define PG8_WAIT_V(n) asm volatile("s_waitcnt vmcnt(" #n ")" ::: "memory")
; #define PG8_BAR __builtin_amdgcn_s_barrier()
; template <class Epi, class Sched, bool ALIGN_EPI = false, bool SP2 = false>
; __device__ __forceinline__ void gemm_phase(PG8_LAS unsigned char* lds, const Gemm g, const Sched& S, const Epi& E) {
;     ...
;         for (int t = 0; t < nt; t += 2) {
;             const bool last = (t == nt - 2);
;             const char* a1 = cA + (size_t)(t + 1) * kstep;
;             const char* a2 = last ? nA : cA + (size_t)(t + 2) * kstep; const char* b2 = last ? nB : cB + (size_t)(t + 2) * kstep;
;             const char* a3 = a2 + kstep; const char* b3 = b2 + kstep;
;             if (last && has_next) S.a_ready(nxt);
;             if constexpr (SP2) {
;             PG8_LDB(B0, 0, 0); PG8_LDB(B1, 0, 1); PG8_SCHED; PG8_LDA(At, 0, 0); PG8_STAGE(PG8_SA(1, 1), a1 + hstep, voffA);
;             PG8_WAIT_V(8); PG8_WAIT_L(0); PG8_BAR; PG8_MMA(0, 0, At, B0); PG8_MMA(0, 1, At, B1); PG8_BAR; PG8_SCHED;
;             PG8_LDA(At, 0, 1); PG8_STAGE(PG8_SB(0, 0), b2, voffB); PG8_STAGE(PG8_SB(0, 1), b2 + hstep, voffB); PG8_STAGE(PG8_SA(0, 0), a2, voffA);
;             PG8_WAIT_V(8); PG8_WAIT_L(0); PG8_BAR; PG8_MMA(1, 0, At, B0); PG8_MMA(1, 1, At, B1); PG8_BAR; PG8_SCHED;
.LBB0_1144:
	s_add_u32 s12, s58, 0xffe00080
	s_addc_u32 s13, s59, -1
	s_add_i32 s84, 0, 0x10000
	s_cmpk_eq_i32 s73, 0x7c
	s_cselect_b32 s63, s18, s13
	s_cselect_b32 s62, s19, s12
	s_cselect_b32 s61, s26, s55
	s_cselect_b32 s60, s47, s49
	s_add_i32 s85, 0, 0x14000
	v_add_u32_e32 v130, s84, v247
	v_add_u32_e32 v158, s85, v247
	ds_read_b128 v[114:117], v130
	ds_read_b128 v[118:121], v130 offset:1024
	ds_read_b128 v[126:129], v130 offset:2048
	ds_read_b128 v[130:133], v130 offset:3072
	ds_read_b128 v[138:141], v158
	ds_read_b128 v[142:145], v158 offset:1024
	ds_read_b128 v[146:149], v158 offset:2048
	ds_read_b128 v[158:161], v158 offset:3072
	v_lshl_add_u64 v[214:215], s[58:59], 0, v[212:213]
	s_add_i32 m0, s57, 0xc000
	ds_read_b128 v[162:165], v249
	ds_read_b128 v[166:169], v249 offset:1024
	ds_read_b128 v[170:173], v249 offset:2048
	ds_read_b128 v[174:177], v249 offset:3072
	ds_read_b128 v[178:181], v249 offset:4096
	ds_read_b128 v[182:185], v249 offset:5120
	ds_read_b128 v[186:189], v249 offset:6144
	ds_read_b128 v[190:193], v249 offset:7168
	global_load_lds_dwordx4 v[214:215], off
	v_lshl_add_u64 v[214:215], s[58:59], 0, v[210:211]
	s_add_i32 m0, s57, 0xe000
	s_nop 0
	global_load_lds_dwordx4 v[214:215], off
	s_waitcnt vmcnt(8)
	s_waitcnt lgkmcnt(0)
	s_barrier
	s_setprio 1
	s_waitcnt lgkmcnt(0)
	v_mfma_f32_16x16x32_bf16 v[154:157], v[114:117], v[162:165], v[154:157]
	v_mfma_f32_16x16x32_bf16 v[150:153], v[126:129], v[162:165], v[150:153]
	v_mfma_f32_16x16x32_bf16 v[110:113], v[114:117], v[170:173], v[110:113]
	v_mfma_f32_16x16x32_bf16 v[106:109], v[126:129], v[170:173], v[106:109]
	v_mfma_f32_16x16x32_bf16 v[92:95], v[114:117], v[178:181], v[92:95]
	v_mfma_f32_16x16x32_bf16 v[88:91], v[126:129], v[178:181], v[88:91]
	v_mfma_f32_16x16x32_bf16 v[76:79], v[114:117], v[186:189], v[76:79]
	v_mfma_f32_16x16x32_bf16 v[72:75], v[126:129], v[186:189], v[72:75]
	v_mfma_f32_16x16x32_bf16 v[154:157], v[118:121], v[166:169], v[154:157]
	v_mfma_f32_16x16x32_bf16 v[150:153], v[130:133], v[166:169], v[150:153]
	v_mfma_f32_16x16x32_bf16 v[110:113], v[118:121], v[174:177], v[110:113]
	v_mfma_f32_16x16x32_bf16 v[106:109], v[130:133], v[174:177], v[106:109]
	v_mfma_f32_16x16x32_bf16 v[92:95], v[118:121], v[182:185], v[92:95]
	v_mfma_f32_16x16x32_bf16 v[88:91], v[130:133], v[182:185], v[88:91]
	v_mfma_f32_16x16x32_bf16 v[76:79], v[118:121], v[190:193], v[76:79]
	v_mfma_f32_16x16x32_bf16 v[72:75], v[130:133], v[190:193], v[72:75]
	s_setprio 0
	s_setprio 1
	v_mfma_f32_16x16x32_bf16 v[134:137], v[138:141], v[162:165], v[134:137]
	v_mfma_f32_16x16x32_bf16 v[122:125], v[146:149], v[162:165], v[122:125]
	v_mfma_f32_16x16x32_bf16 v[102:105], v[138:141], v[170:173], v[102:105]
	v_mfma_f32_16x16x32_bf16 v[98:101], v[146:149], v[170:173], v[98:101]
	v_mfma_f32_16x16x32_bf16 v[84:87], v[138:141], v[178:181], v[84:87]
	v_mfma_f32_16x16x32_bf16 v[80:83], v[146:149], v[178:181], v[80:83]
	v_mfma_f32_16x16x32_bf16 v[68:71], v[138:141], v[186:189], v[68:71]
	v_mfma_f32_16x16x32_bf16 v[64:67], v[146:149], v[186:189], v[64:67]
	v_mfma_f32_16x16x32_bf16 v[134:137], v[142:145], v[166:169], v[134:137]
	v_mfma_f32_16x16x32_bf16 v[122:125], v[158:161], v[166:169], v[122:125]
	v_mfma_f32_16x16x32_bf16 v[102:105], v[142:145], v[174:177], v[102:105]
	v_mfma_f32_16x16x32_bf16 v[98:101], v[158:161], v[174:177], v[98:101]
	v_mfma_f32_16x16x32_bf16 v[84:87], v[142:145], v[182:185], v[84:87]
	v_mfma_f32_16x16x32_bf16 v[80:83], v[158:161], v[182:185], v[80:83]
	v_mfma_f32_16x16x32_bf16 v[68:71], v[142:145], v[190:193], v[68:71]
	v_mfma_f32_16x16x32_bf16 v[64:67], v[158:161], v[190:193], v[64:67]
	s_setprio 0
	s_barrier
	s_add_i32 s12, s84, s11
	v_lshl_add_u64 v[214:215], s[60:61], 0, v[204:205]
	s_mov_b32 m0, s12
	ds_read_b128 v[162:165], v249 offset:16384
	ds_read_b128 v[166:169], v249 offset:17408
	ds_read_b128 v[170:173], v249 offset:18432
	ds_read_b128 v[174:177], v249 offset:19456
	ds_read_b128 v[178:181], v249 offset:20480
	ds_read_b128 v[182:185], v249 offset:21504
	ds_read_b128 v[186:189], v249 offset:22528
	ds_read_b128 v[190:193], v249 offset:23552
	global_load_lds_dwordx4 v[214:215], off
	s_add_i32 m0, s12, 0x2000
	s_add_u32 s12, s60, 0x200000
	v_lshl_add_u64 v[216:217], s[60:61], 0, v[208:209]
	s_addc_u32 s13, s61, 0
	s_add_i32 s84, s85, s11
	global_load_lds_dwordx4 v[216:217], off
	v_lshl_add_u64 v[218:219], s[12:13], 0, v[204:205]
	s_mov_b32 m0, s84
	v_lshl_add_u64 v[220:221], s[62:63], 0, v[206:207]
	global_load_lds_dwordx4 v[218:219], off
	v_lshl_add_u64 v[218:219], s[12:13], 0, v[208:209]
	s_add_i32 m0, s84, 0x2000
	s_nop 0
	global_load_lds_dwordx4 v[218:219], off
	v_lshl_add_u64 v[218:219], s[62:63], 0, v[202:203]
	s_mov_b32 m0, s57
	s_nop 0
	global_load_lds_dwordx4 v[218:219], off
	s_mov_b32 m0, s65
	s_nop 0
	global_load_lds_dwordx4 v[220:221], off
	s_waitcnt vmcnt(8)
	s_waitcnt lgkmcnt(0)
	s_barrier
; #define PG8_STAGE(bufoff, gbase, voff) do { _Pragma("unroll") for (int _i = 0; _i < 2; ++_i) \
;         __builtin_amdgcn_global_load_lds((const unsigned*)((const char*)(gbase) + (voff)[_i]), (PG8_LAS unsigned*)(lds + (bufoff) + ldsw + _i * 8192), 16, 0, 0); } while (0)
; #define PG8_LDA(dst, b, h) do { _Pragma("unroll") for (int m = 0; m < 4; ++m) _Pragma("unroll") for (int k = 0; k < 2; ++k) dst[m][k] = *(const PG8_LAS bf16x8*)(lds + PG8_SA(b, h) + aoff + m * 2048 + k * 1024); } while (0)
; #define PG8_LDB(dst, b, h) do { _Pragma("unroll") for (int n = 0; n < 2; ++n) _Pragma("unroll") for (int k = 0; k < 2; ++k) dst[n][k] = *(const PG8_LAS bf16x8*)(lds + PG8_SB(b, h) + boff + n * 2048 + k * 1024); } while (0)
; #define PG8_MMA(ai, bj, At, Bt) do { __builtin_amdgcn_s_setprio(1); _Pragma("unroll") for (int m = 0; m < 4; ++m) _Pragma("unroll") for (int n = 0; n < 2; ++n) _Pragma("unroll") for (int k = 0; k < 2; ++k) \
;         acc[ai][bj][m][n] = __builtin_amdgcn_mfma_f32_16x16x32_bf16(Bt[n][k], At[m][k], acc[ai][bj][m][n], 0, 0, 0); __builtin_amdgcn_s_setprio(0); } while (0)
; #define PG8_WAIT_V(n) asm volatile("s_waitcnt vmcnt(" #n ")" ::: "memory")
; #define PG8_WAIT_L(n) asm volatile("s_waitcnt lgkmcnt(" #n ")" ::: "memory")
; #define PG8_BAR __builtin_amdgcn_s_barrier()
; #define PG8_SCHED __builtin_amdgcn_sched_barrier(0)
; template <class Epi, class Sched, bool ALIGN_EPI = false, bool SP2 = false>
; __device__ __forceinline__ void gemm_phase(PG8_LAS unsigned char* lds, const Gemm g, const Sched& S, const Epi& E) {
;     ...
;             PG8_WAIT_V(8); PG8_WAIT_L(0); PG8_BAR; PG8_MMA(1, 0, At, B0); PG8_MMA(1, 1, At, B1); PG8_BAR; PG8_SCHED;
;             PG8_LDB(B0, 1, 0); PG8_LDB(B1, 1, 1); PG8_SCHED; PG8_LDA(At, 1, 0); PG8_STAGE(PG8_SA(0, 1), a2 + hstep, voffA);
;             PG8_WAIT_V(8); PG8_WAIT_L(0); PG8_BAR; PG8_MMA(0, 0, At, B0); PG8_MMA(0, 1, At, B1); PG8_BAR; PG8_SCHED;
	s_setprio 1
	s_waitcnt lgkmcnt(0)
	v_mfma_f32_16x16x32_bf16 v[60:63], v[114:117], v[162:165], v[60:63]
	v_mfma_f32_16x16x32_bf16 v[56:59], v[126:129], v[162:165], v[56:59]
	v_mfma_f32_16x16x32_bf16 v[44:47], v[114:117], v[170:173], v[44:47]
	v_mfma_f32_16x16x32_bf16 v[40:43], v[126:129], v[170:173], v[40:43]
	v_mfma_f32_16x16x32_bf16 v[28:31], v[114:117], v[178:181], v[28:31]
	v_mfma_f32_16x16x32_bf16 v[24:27], v[126:129], v[178:181], v[24:27]
	v_mfma_f32_16x16x32_bf16 v[12:15], v[114:117], v[186:189], v[12:15]
	v_mfma_f32_16x16x32_bf16 v[8:11], v[126:129], v[186:189], v[8:11]
	v_mfma_f32_16x16x32_bf16 v[60:63], v[118:121], v[166:169], v[60:63]
	v_mfma_f32_16x16x32_bf16 v[56:59], v[130:133], v[166:169], v[56:59]
	v_mfma_f32_16x16x32_bf16 v[44:47], v[118:121], v[174:177], v[44:47]
	v_mfma_f32_16x16x32_bf16 v[40:43], v[130:133], v[174:177], v[40:43]
	v_mfma_f32_16x16x32_bf16 v[28:31], v[118:121], v[182:185], v[28:31]
	v_mfma_f32_16x16x32_bf16 v[24:27], v[130:133], v[182:185], v[24:27]
	v_mfma_f32_16x16x32_bf16 v[12:15], v[118:121], v[190:193], v[12:15]
	v_mfma_f32_16x16x32_bf16 v[8:11], v[130:133], v[190:193], v[8:11]
	s_setprio 0
	s_setprio 1
	v_mfma_f32_16x16x32_bf16 v[52:55], v[138:141], v[162:165], v[52:55]
	v_mfma_f32_16x16x32_bf16 v[48:51], v[146:149], v[162:165], v[48:51]
	v_mfma_f32_16x16x32_bf16 v[36:39], v[138:141], v[170:173], v[36:39]
	v_mfma_f32_16x16x32_bf16 v[32:35], v[146:149], v[170:173], v[32:35]
	v_mfma_f32_16x16x32_bf16 v[20:23], v[138:141], v[178:181], v[20:23]
	v_mfma_f32_16x16x32_bf16 v[16:19], v[146:149], v[178:181], v[16:19]
	v_mfma_f32_16x16x32_bf16 v[4:7], v[138:141], v[186:189], v[4:7]
	v_mfma_f32_16x16x32_bf16 v[0:3], v[146:149], v[186:189], v[0:3]
	v_mfma_f32_16x16x32_bf16 v[52:55], v[142:145], v[166:169], v[52:55]
	v_mfma_f32_16x16x32_bf16 v[48:51], v[158:161], v[166:169], v[48:51]
	v_mfma_f32_16x16x32_bf16 v[36:39], v[142:145], v[174:177], v[36:39]
	v_mfma_f32_16x16x32_bf16 v[32:35], v[158:161], v[174:177], v[32:35]
	v_mfma_f32_16x16x32_bf16 v[20:23], v[142:145], v[182:185], v[20:23]
	v_mfma_f32_16x16x32_bf16 v[16:19], v[158:161], v[182:185], v[16:19]
	v_mfma_f32_16x16x32_bf16 v[4:7], v[142:145], v[190:193], v[4:7]
	v_mfma_f32_16x16x32_bf16 v[0:3], v[158:161], v[190:193], v[0:3]
	s_setprio 0
	s_barrier
	s_add_i32 s84, 0, 0x18000
	s_add_i32 s85, 0, 0x1c000
	v_add_u32_e32 v130, s84, v247
	v_add_u32_e32 v158, s85, v247
	ds_read_b128 v[114:117], v130
	ds_read_b128 v[118:121], v130 offset:1024
	ds_read_b128 v[126:129], v130 offset:2048
	ds_read_b128 v[130:133], v130 offset:3072
	ds_read_b128 v[138:141], v158
	ds_read_b128 v[142:145], v158 offset:1024
	ds_read_b128 v[146:149], v158 offset:2048
	ds_read_b128 v[158:161], v158 offset:3072
	s_add_u32 s12, s62, 0x200000
	s_addc_u32 s13, s63, 0
	s_mov_b32 m0, s66
	v_lshl_add_u64 v[222:223], s[12:13], 0, v[202:203]
	ds_read_b128 v[162:165], v249 offset:32768
	ds_read_b128 v[166:169], v249 offset:33792
	ds_read_b128 v[170:173], v249 offset:34816
	ds_read_b128 v[174:177], v249 offset:35840
	ds_read_b128 v[178:181], v249 offset:36864
	ds_read_b128 v[182:185], v249 offset:37888
	ds_read_b128 v[186:189], v249 offset:38912
	ds_read_b128 v[190:193], v249 offset:39936
	global_load_lds_dwordx4 v[222:223], off
	v_lshl_add_u64 v[222:223], s[12:13], 0, v[206:207]
	s_mov_b32 m0, s67
	s_nop 0
	global_load_lds_dwordx4 v[222:223], off
	s_waitcnt vmcnt(8)
	s_waitcnt lgkmcnt(0)
	s_barrier
	s_setprio 1
	s_waitcnt lgkmcnt(0)
	v_mfma_f32_16x16x32_bf16 v[154:157], v[114:117], v[162:165], v[154:157]
	v_mfma_f32_16x16x32_bf16 v[150:153], v[126:129], v[162:165], v[150:153]
	v_mfma_f32_16x16x32_bf16 v[110:113], v[114:117], v[170:173], v[110:113]
	v_mfma_f32_16x16x32_bf16 v[106:109], v[126:129], v[170:173], v[106:109]
	v_mfma_f32_16x16x32_bf16 v[92:95], v[114:117], v[178:181], v[92:95]
	v_mfma_f32_16x16x32_bf16 v[88:91], v[126:129], v[178:181], v[88:91]
	v_mfma_f32_16x16x32_bf16 v[76:79], v[114:117], v[186:189], v[76:79]
	v_mfma_f32_16x16x32_bf16 v[72:75], v[126:129], v[186:189], v[72:75]
	v_mfma_f32_16x16x32_bf16 v[154:157], v[118:121], v[166:169], v[154:157]
	v_mfma_f32_16x16x32_bf16 v[150:153], v[130:133], v[166:169], v[150:153]
	v_mfma_f32_16x16x32_bf16 v[110:113], v[118:121], v[174:177], v[110:113]
	v_mfma_f32_16x16x32_bf16 v[106:109], v[130:133], v[174:177], v[106:109]
	v_mfma_f32_16x16x32_bf16 v[92:95], v[118:121], v[182:185], v[92:95]
	v_mfma_f32_16x16x32_bf16 v[88:91], v[130:133], v[182:185], v[88:91]
	v_mfma_f32_16x16x32_bf16 v[76:79], v[118:121], v[190:193], v[76:79]
	v_mfma_f32_16x16x32_bf16 v[72:75], v[130:133], v[190:193], v[72:75]
	s_setprio 0
	s_setprio 1
	v_mfma_f32_16x16x32_bf16 v[134:137], v[138:141], v[162:165], v[134:137]
	v_mfma_f32_16x16x32_bf16 v[122:125], v[146:149], v[162:165], v[122:125]
	v_mfma_f32_16x16x32_bf16 v[102:105], v[138:141], v[170:173], v[102:105]
	v_mfma_f32_16x16x32_bf16 v[98:101], v[146:149], v[170:173], v[98:101]
	v_mfma_f32_16x16x32_bf16 v[84:87], v[138:141], v[178:181], v[84:87]
	v_mfma_f32_16x16x32_bf16 v[80:83], v[146:149], v[178:181], v[80:83]
	v_mfma_f32_16x16x32_bf16 v[68:71], v[138:141], v[186:189], v[68:71]
	v_mfma_f32_16x16x32_bf16 v[64:67], v[146:149], v[186:189], v[64:67]
	v_mfma_f32_16x16x32_bf16 v[134:137], v[142:145], v[166:169], v[134:137]
	v_mfma_f32_16x16x32_bf16 v[122:125], v[158:161], v[166:169], v[122:125]
	v_mfma_f32_16x16x32_bf16 v[102:105], v[142:145], v[174:177], v[102:105]
	v_mfma_f32_16x16x32_bf16 v[98:101], v[158:161], v[174:177], v[98:101]
	v_mfma_f32_16x16x32_bf16 v[84:87], v[142:145], v[182:185], v[84:87]
	v_mfma_f32_16x16x32_bf16 v[80:83], v[158:161], v[182:185], v[80:83]
	v_mfma_f32_16x16x32_bf16 v[68:71], v[142:145], v[190:193], v[68:71]
	v_mfma_f32_16x16x32_bf16 v[64:67], v[158:161], v[190:193], v[64:67]
	s_setprio 0
	s_barrier
; #define PG8_STAGE(bufoff, gbase, voff) do { _Pragma("unroll") for (int _i = 0; _i < 2; ++_i) \
;         __builtin_amdgcn_global_load_lds((const unsigned*)((const char*)(gbase) + (voff)[_i]), (PG8_LAS unsigned*)(lds + (bufoff) + ldsw + _i * 8192), 16, 0, 0); } while (0)
; #define PG8_LDA(dst, b, h) do { _Pragma("unroll") for (int m = 0; m < 4; ++m) _Pragma("unroll") for (int k = 0; k < 2; ++k) dst[m][k] = *(const PG8_LAS bf16x8*)(lds + PG8_SA(b, h) + aoff + m * 2048 + k * 1024); } while (0)
; #define PG8_MMA(ai, bj, At, Bt) do { __builtin_amdgcn_s_setprio(1); _Pragma("unroll") for (int m = 0; m < 4; ++m) _Pragma("unroll") for (int n = 0; n < 2; ++n) _Pragma("unroll") for (int k = 0; k < 2; ++k) \
;         acc[ai][bj][m][n] = __builtin_amdgcn_mfma_f32_16x16x32_bf16(Bt[n][k], At[m][k], acc[ai][bj][m][n], 0, 0, 0); __builtin_amdgcn_s_setprio(0); } while (0)
; #define PG8_WAIT_V(n) asm volatile("s_waitcnt vmcnt(" #n ")" ::: "memory")
; #define PG8_WAIT_L(n) asm volatile("s_waitcnt lgkmcnt(" #n ")" ::: "memory")
; #define PG8_BAR __builtin_amdgcn_s_barrier()
; #define PG8_SCHED __builtin_amdgcn_sched_barrier(0)
; template <class Epi, class Sched, bool ALIGN_EPI = false, bool SP2 = false>
; __device__ __forceinline__ void gemm_phase(PG8_LAS unsigned char* lds, const Gemm g, const Sched& S, const Epi& E) {
;     ...
;         for (int t = 0; t < nt; t += 2) {
;             const bool last = (t == nt - 2);
;     ...
;             PG8_LDA(At, 1, 1); PG8_STAGE(PG8_SB(1, 0), b3, voffB); PG8_STAGE(PG8_SB(1, 1), b3 + hstep, voffB); PG8_STAGE(PG8_SA(1, 0), a3, voffA);
;             PG8_WAIT_V(8); PG8_WAIT_L(0); PG8_BAR; PG8_MMA(1, 0, At, B0); PG8_MMA(1, 1, At, B1); PG8_BAR; PG8_SCHED;
	s_add_i32 s12, s84, s11
	v_lshl_add_u64 v[214:215], v[214:215], 0, s[36:37]
	s_mov_b32 m0, s12
	ds_read_b128 v[162:165], v249 offset:49152
	ds_read_b128 v[166:169], v249 offset:50176
	ds_read_b128 v[170:173], v249 offset:51200
	ds_read_b128 v[174:177], v249 offset:52224
	ds_read_b128 v[178:181], v249 offset:53248
	ds_read_b128 v[182:185], v249 offset:54272
	ds_read_b128 v[186:189], v249 offset:55296
	ds_read_b128 v[190:193], v249 offset:56320
	global_load_lds_dwordx4 v[214:215], off
	s_add_i32 m0, s12, 0x2000
	s_add_u32 s12, s60, 0x200080
	v_lshl_add_u64 v[214:215], v[216:217], 0, s[36:37]
	s_addc_u32 s13, s61, 0
	s_add_i32 s60, s85, s11
	global_load_lds_dwordx4 v[214:215], off
	v_lshl_add_u64 v[214:215], s[12:13], 0, v[204:205]
	s_mov_b32 m0, s60
	s_nop 0
	global_load_lds_dwordx4 v[214:215], off
	v_lshl_add_u64 v[214:215], s[12:13], 0, v[208:209]
	s_add_i32 m0, s60, 0x2000
	s_nop 0
	global_load_lds_dwordx4 v[214:215], off
	v_lshl_add_u64 v[214:215], v[218:219], 0, s[36:37]
	s_mov_b32 m0, s69
	s_nop 0
	global_load_lds_dwordx4 v[214:215], off
	v_lshl_add_u64 v[214:215], v[220:221], 0, s[36:37]
	s_mov_b32 m0, s70
	s_nop 0
	global_load_lds_dwordx4 v[214:215], off
	s_waitcnt vmcnt(8)
	s_waitcnt lgkmcnt(0)
	s_barrier
	s_setprio 1
	s_waitcnt lgkmcnt(0)
	v_mfma_f32_16x16x32_bf16 v[60:63], v[114:117], v[162:165], v[60:63]
	v_mfma_f32_16x16x32_bf16 v[56:59], v[126:129], v[162:165], v[56:59]
	v_mfma_f32_16x16x32_bf16 v[44:47], v[114:117], v[170:173], v[44:47]
	v_mfma_f32_16x16x32_bf16 v[40:43], v[126:129], v[170:173], v[40:43]
	v_mfma_f32_16x16x32_bf16 v[28:31], v[114:117], v[178:181], v[28:31]
	v_mfma_f32_16x16x32_bf16 v[24:27], v[126:129], v[178:181], v[24:27]
	v_mfma_f32_16x16x32_bf16 v[12:15], v[114:117], v[186:189], v[12:15]
	v_mfma_f32_16x16x32_bf16 v[8:11], v[126:129], v[186:189], v[8:11]
	v_mfma_f32_16x16x32_bf16 v[60:63], v[118:121], v[166:169], v[60:63]
	v_mfma_f32_16x16x32_bf16 v[56:59], v[130:133], v[166:169], v[56:59]
	v_mfma_f32_16x16x32_bf16 v[44:47], v[118:121], v[174:177], v[44:47]
	v_mfma_f32_16x16x32_bf16 v[40:43], v[130:133], v[174:177], v[40:43]
	v_mfma_f32_16x16x32_bf16 v[28:31], v[118:121], v[182:185], v[28:31]
	v_mfma_f32_16x16x32_bf16 v[24:27], v[130:133], v[182:185], v[24:27]
	v_mfma_f32_16x16x32_bf16 v[12:15], v[118:121], v[190:193], v[12:15]
	v_mfma_f32_16x16x32_bf16 v[8:11], v[130:133], v[190:193], v[8:11]
	s_setprio 0
	s_setprio 1
	v_mfma_f32_16x16x32_bf16 v[52:55], v[138:141], v[162:165], v[52:55]
	v_mfma_f32_16x16x32_bf16 v[48:51], v[146:149], v[162:165], v[48:51]
	v_mfma_f32_16x16x32_bf16 v[36:39], v[138:141], v[170:173], v[36:39]
	v_mfma_f32_16x16x32_bf16 v[32:35], v[146:149], v[170:173], v[32:35]
	v_mfma_f32_16x16x32_bf16 v[20:23], v[138:141], v[178:181], v[20:23]
	v_mfma_f32_16x16x32_bf16 v[16:19], v[146:149], v[178:181], v[16:19]
	v_mfma_f32_16x16x32_bf16 v[4:7], v[138:141], v[186:189], v[4:7]
	v_mfma_f32_16x16x32_bf16 v[0:3], v[146:149], v[186:189], v[0:3]
	v_mfma_f32_16x16x32_bf16 v[52:55], v[142:145], v[166:169], v[52:55]
	v_mfma_f32_16x16x32_bf16 v[48:51], v[158:161], v[166:169], v[48:51]
	v_mfma_f32_16x16x32_bf16 v[36:39], v[142:145], v[174:177], v[36:39]
	v_mfma_f32_16x16x32_bf16 v[32:35], v[158:161], v[174:177], v[32:35]
	v_mfma_f32_16x16x32_bf16 v[20:23], v[142:145], v[182:185], v[20:23]
	v_mfma_f32_16x16x32_bf16 v[16:19], v[158:161], v[182:185], v[16:19]
	v_mfma_f32_16x16x32_bf16 v[4:7], v[142:145], v[190:193], v[4:7]
	v_mfma_f32_16x16x32_bf16 v[0:3], v[158:161], v[190:193], v[0:3]
	s_setprio 0
	s_add_i32 s73, s73, 2
	s_add_u32 s49, s49, 0x100
	s_addc_u32 s55, s55, 0
	s_add_u32 s58, s58, 0x100
	s_addc_u32 s59, s59, 0
	s_barrier
	s_cmpk_gt_u32 s73, 0x7d
	s_cbranch_scc0 .LBB0_1144
	s_and_b64 vcc, exec, s[14:15]
	s_cbranch_vccz .LBB0_1147
	s_barrier
